# v28
# speedup vs baseline: 1.0545x; 1.0048x over previous
; __device__ __forceinline__ float bflo(unsigned w) { return __uint_as_float(w << 16); }
; __device__ __forceinline__ float bfhi(unsigned w) { return __uint_as_float(w & 0xffff0000u); }
; __device__ __forceinline__ void sg_mfma_phase(int wave_s, const bf16_t* Z, bf16_t* SGO, const float* sgw, const float* sgb, const float* lng, const float* lnb, LAS unsigned char* lds) {
;     ...
;         for (int rr = 0; rr < 16; ++rr) { const int j = wave * 16 + rr; const bf16_t* vp = Z + (row0 + j) * N1 + 5632 + lane * 16;
;             const u32x4 a = *(const u32x4*)vp, b = *(const u32x4*)(vp + 8); float f[16];
;             f[0] = bflo(a.x); f[1] = bfhi(a.x); f[2] = bflo(a.y); f[3] = bfhi(a.y); f[4] = bflo(a.z); f[5] = bfhi(a.z); f[6] = bflo(a.w); f[7] = bfhi(a.w);
;             f[8] = bflo(b.x); f[9] = bfhi(b.x); f[10] = bflo(b.y); f[11] = bfhi(b.y); f[12] = bflo(b.z); f[13] = bfhi(b.z); f[14] = bflo(b.w); f[15] = bfhi(b.w);
;             float s = 0.f;
; #pragma unroll
;             for (int i = 0; i < 16; ++i) s += f[i];
.LBB0_243:
	s_waitcnt lgkmcnt(0)
	s_mov_b64 s[10:11], 0x3400
	global_load_dwordx4 v[170:173], v[0:1], off
	global_load_dwordx4 v[174:177], v[0:1], off offset:16
	v_lshl_add_u64 v[0:1], v[0:1], 0, s[10:11]
	global_load_dwordx4 v[178:181], v[0:1], off
	global_load_dwordx4 v[182:185], v[0:1], off offset:16
	v_lshl_add_u64 v[0:1], v[0:1], 0, s[10:11]
	global_load_dwordx4 v[186:189], v[0:1], off
	global_load_dwordx4 v[190:193], v[0:1], off offset:16
	v_lshl_add_u64 v[0:1], v[0:1], 0, s[10:11]
	global_load_dwordx4 v[194:197], v[0:1], off
	global_load_dwordx4 v[198:201], v[0:1], off offset:16
	v_lshl_add_u64 v[0:1], v[0:1], 0, s[10:11]
	global_load_dwordx4 v[202:205], v[0:1], off
	global_load_dwordx4 v[206:209], v[0:1], off offset:16
	v_lshl_add_u64 v[0:1], v[0:1], 0, s[10:11]
	global_load_dwordx4 v[210:213], v[0:1], off
	global_load_dwordx4 v[214:217], v[0:1], off offset:16
	v_lshl_add_u64 v[0:1], v[0:1], 0, s[10:11]
	global_load_dwordx4 v[218:221], v[0:1], off
	global_load_dwordx4 v[222:225], v[0:1], off offset:16
	v_lshl_add_u64 v[0:1], v[0:1], 0, s[10:11]
	global_load_dwordx4 v[226:229], v[0:1], off
	global_load_dwordx4 v[230:233], v[0:1], off offset:16
	v_lshl_add_u64 v[0:1], v[0:1], 0, s[10:11]
	s_waitcnt vmcnt(14)
	v_lshlrev_b32_e32 v10, 16, v170
	v_add_f32_e32 v234, 0, v10
	v_and_b32_e32 v11, 0xffff0000, v170
	v_add_f32_e32 v234, v234, v11
	v_lshlrev_b32_e32 v10, 16, v171
	v_add_f32_e32 v234, v234, v10
	v_and_b32_e32 v11, 0xffff0000, v171
	v_add_f32_e32 v234, v234, v11
	v_lshlrev_b32_e32 v10, 16, v172
	v_add_f32_e32 v234, v234, v10
	v_and_b32_e32 v11, 0xffff0000, v172
	v_add_f32_e32 v234, v234, v11
	v_lshlrev_b32_e32 v10, 16, v173
	v_add_f32_e32 v234, v234, v10
	v_and_b32_e32 v11, 0xffff0000, v173
	v_add_f32_e32 v234, v234, v11
	v_lshlrev_b32_e32 v10, 16, v174
	v_add_f32_e32 v234, v234, v10
	v_and_b32_e32 v11, 0xffff0000, v174
	v_add_f32_e32 v234, v234, v11
	v_lshlrev_b32_e32 v10, 16, v175
	v_add_f32_e32 v234, v234, v10
	v_and_b32_e32 v11, 0xffff0000, v175
	v_add_f32_e32 v234, v234, v11
	v_lshlrev_b32_e32 v10, 16, v176
	v_add_f32_e32 v234, v234, v10
	v_and_b32_e32 v11, 0xffff0000, v176
	v_add_f32_e32 v234, v234, v11
	v_lshlrev_b32_e32 v10, 16, v177
	v_add_f32_e32 v234, v234, v10
	v_and_b32_e32 v11, 0xffff0000, v177
	v_add_f32_e32 v234, v234, v11
	s_waitcnt vmcnt(12)
	v_lshlrev_b32_e32 v10, 16, v178
	v_add_f32_e32 v235, 0, v10
	v_and_b32_e32 v11, 0xffff0000, v178
	v_add_f32_e32 v235, v235, v11
	v_lshlrev_b32_e32 v10, 16, v179
	v_add_f32_e32 v235, v235, v10
	v_and_b32_e32 v11, 0xffff0000, v179
	v_add_f32_e32 v235, v235, v11
	v_lshlrev_b32_e32 v10, 16, v180
	v_add_f32_e32 v235, v235, v10
	v_and_b32_e32 v11, 0xffff0000, v180
	v_add_f32_e32 v235, v235, v11
	v_lshlrev_b32_e32 v10, 16, v181
	v_add_f32_e32 v235, v235, v10
	v_and_b32_e32 v11, 0xffff0000, v181
	v_add_f32_e32 v235, v235, v11
	v_lshlrev_b32_e32 v10, 16, v182
	v_add_f32_e32 v235, v235, v10
	v_and_b32_e32 v11, 0xffff0000, v182
	v_add_f32_e32 v235, v235, v11
	v_lshlrev_b32_e32 v10, 16, v183
	v_add_f32_e32 v235, v235, v10
	v_and_b32_e32 v11, 0xffff0000, v183
	v_add_f32_e32 v235, v235, v11
	v_lshlrev_b32_e32 v10, 16, v184
	v_add_f32_e32 v235, v235, v10
	v_and_b32_e32 v11, 0xffff0000, v184
	v_add_f32_e32 v235, v235, v11
	v_lshlrev_b32_e32 v10, 16, v185
	v_add_f32_e32 v235, v235, v10
	v_and_b32_e32 v11, 0xffff0000, v185
	v_add_f32_e32 v235, v235, v11
	s_waitcnt vmcnt(10)
	v_lshlrev_b32_e32 v10, 16, v186
	v_add_f32_e32 v236, 0, v10
	v_and_b32_e32 v11, 0xffff0000, v186
	v_add_f32_e32 v236, v236, v11
	v_lshlrev_b32_e32 v10, 16, v187
	v_add_f32_e32 v236, v236, v10
	v_and_b32_e32 v11, 0xffff0000, v187
	v_add_f32_e32 v236, v236, v11
	v_lshlrev_b32_e32 v10, 16, v188
	v_add_f32_e32 v236, v236, v10
	v_and_b32_e32 v11, 0xffff0000, v188
	v_add_f32_e32 v236, v236, v11
	v_lshlrev_b32_e32 v10, 16, v189
	v_add_f32_e32 v236, v236, v10
	v_and_b32_e32 v11, 0xffff0000, v189
	v_add_f32_e32 v236, v236, v11
	v_lshlrev_b32_e32 v10, 16, v190
	v_add_f32_e32 v236, v236, v10
	v_and_b32_e32 v11, 0xffff0000, v190
	v_add_f32_e32 v236, v236, v11
	v_lshlrev_b32_e32 v10, 16, v191
	v_add_f32_e32 v236, v236, v10
	v_and_b32_e32 v11, 0xffff0000, v191
	v_add_f32_e32 v236, v236, v11
	v_lshlrev_b32_e32 v10, 16, v192
	v_add_f32_e32 v236, v236, v10
	v_and_b32_e32 v11, 0xffff0000, v192
	v_add_f32_e32 v236, v236, v11
	v_lshlrev_b32_e32 v10, 16, v193
	v_add_f32_e32 v236, v236, v10
	v_and_b32_e32 v11, 0xffff0000, v193
	v_add_f32_e32 v236, v236, v11
	s_waitcnt vmcnt(8)
	v_lshlrev_b32_e32 v10, 16, v194
	v_add_f32_e32 v237, 0, v10
	v_and_b32_e32 v11, 0xffff0000, v194
	v_add_f32_e32 v237, v237, v11
	v_lshlrev_b32_e32 v10, 16, v195
	v_add_f32_e32 v237, v237, v10
	v_and_b32_e32 v11, 0xffff0000, v195
	v_add_f32_e32 v237, v237, v11
	v_lshlrev_b32_e32 v10, 16, v196
	v_add_f32_e32 v237, v237, v10
	v_and_b32_e32 v11, 0xffff0000, v196
	v_add_f32_e32 v237, v237, v11
	v_lshlrev_b32_e32 v10, 16, v197
	v_add_f32_e32 v237, v237, v10
	v_and_b32_e32 v11, 0xffff0000, v197
	v_add_f32_e32 v237, v237, v11
	v_lshlrev_b32_e32 v10, 16, v198
	v_add_f32_e32 v237, v237, v10
	v_and_b32_e32 v11, 0xffff0000, v198
	v_add_f32_e32 v237, v237, v11
	v_lshlrev_b32_e32 v10, 16, v199
	v_add_f32_e32 v237, v237, v10
	v_and_b32_e32 v11, 0xffff0000, v199
	v_add_f32_e32 v237, v237, v11
	v_lshlrev_b32_e32 v10, 16, v200
	v_add_f32_e32 v237, v237, v10
	v_and_b32_e32 v11, 0xffff0000, v200
	v_add_f32_e32 v237, v237, v11
	v_lshlrev_b32_e32 v10, 16, v201
	v_add_f32_e32 v237, v237, v10
	v_and_b32_e32 v11, 0xffff0000, v201
	v_add_f32_e32 v237, v237, v11
	s_waitcnt vmcnt(6)
; __device__ __forceinline__ float wave_sum(float v, int lane) { for (int o = 32; o >= 1; o >>= 1) v += shx(v, o, lane); return v; }
; __device__ __forceinline__ void sg_mfma_phase(int wave_s, const bf16_t* Z, bf16_t* SGO, const float* sgw, const float* sgb, const float* lng, const float* lnb, LAS unsigned char* lds) {
;     ...
; #pragma unroll
;             for (int i = 0; i < 16; ++i) s += f[i];
;             const float mu = wave_sum(s, lane) * (1.0f / 1024.0f); float q = 0.f;
	v_lshlrev_b32_e32 v10, 16, v202
	v_add_f32_e32 v238, 0, v10
	v_and_b32_e32 v11, 0xffff0000, v202
	v_add_f32_e32 v238, v238, v11
	v_lshlrev_b32_e32 v10, 16, v203
	v_add_f32_e32 v238, v238, v10
	v_and_b32_e32 v11, 0xffff0000, v203
	v_add_f32_e32 v238, v238, v11
	v_lshlrev_b32_e32 v10, 16, v204
	v_add_f32_e32 v238, v238, v10
	v_and_b32_e32 v11, 0xffff0000, v204
	v_add_f32_e32 v238, v238, v11
	v_lshlrev_b32_e32 v10, 16, v205
	v_add_f32_e32 v238, v238, v10
	v_and_b32_e32 v11, 0xffff0000, v205
	v_add_f32_e32 v238, v238, v11
	v_lshlrev_b32_e32 v10, 16, v206
	v_add_f32_e32 v238, v238, v10
	v_and_b32_e32 v11, 0xffff0000, v206
	v_add_f32_e32 v238, v238, v11
	v_lshlrev_b32_e32 v10, 16, v207
	v_add_f32_e32 v238, v238, v10
	v_and_b32_e32 v11, 0xffff0000, v207
	v_add_f32_e32 v238, v238, v11
	v_lshlrev_b32_e32 v10, 16, v208
	v_add_f32_e32 v238, v238, v10
	v_and_b32_e32 v11, 0xffff0000, v208
	v_add_f32_e32 v238, v238, v11
	v_lshlrev_b32_e32 v10, 16, v209
	v_add_f32_e32 v238, v238, v10
	v_and_b32_e32 v11, 0xffff0000, v209
	v_add_f32_e32 v238, v238, v11
	s_waitcnt vmcnt(4)
	v_lshlrev_b32_e32 v10, 16, v210
	v_add_f32_e32 v239, 0, v10
	v_and_b32_e32 v11, 0xffff0000, v210
	v_add_f32_e32 v239, v239, v11
	v_lshlrev_b32_e32 v10, 16, v211
	v_add_f32_e32 v239, v239, v10
	v_and_b32_e32 v11, 0xffff0000, v211
	v_add_f32_e32 v239, v239, v11
	v_lshlrev_b32_e32 v10, 16, v212
	v_add_f32_e32 v239, v239, v10
	v_and_b32_e32 v11, 0xffff0000, v212
	v_add_f32_e32 v239, v239, v11
	v_lshlrev_b32_e32 v10, 16, v213
	v_add_f32_e32 v239, v239, v10
	v_and_b32_e32 v11, 0xffff0000, v213
	v_add_f32_e32 v239, v239, v11
	v_lshlrev_b32_e32 v10, 16, v214
	v_add_f32_e32 v239, v239, v10
	v_and_b32_e32 v11, 0xffff0000, v214
	v_add_f32_e32 v239, v239, v11
	v_lshlrev_b32_e32 v10, 16, v215
	v_add_f32_e32 v239, v239, v10
	v_and_b32_e32 v11, 0xffff0000, v215
	v_add_f32_e32 v239, v239, v11
	v_lshlrev_b32_e32 v10, 16, v216
	v_add_f32_e32 v239, v239, v10
	v_and_b32_e32 v11, 0xffff0000, v216
	v_add_f32_e32 v239, v239, v11
	v_lshlrev_b32_e32 v10, 16, v217
	v_add_f32_e32 v239, v239, v10
	v_and_b32_e32 v11, 0xffff0000, v217
	v_add_f32_e32 v239, v239, v11
	s_waitcnt vmcnt(2)
	v_lshlrev_b32_e32 v10, 16, v218
	v_add_f32_e32 v240, 0, v10
	v_and_b32_e32 v11, 0xffff0000, v218
	v_add_f32_e32 v240, v240, v11
	v_lshlrev_b32_e32 v10, 16, v219
	v_add_f32_e32 v240, v240, v10
	v_and_b32_e32 v11, 0xffff0000, v219
	v_add_f32_e32 v240, v240, v11
	v_lshlrev_b32_e32 v10, 16, v220
	v_add_f32_e32 v240, v240, v10
	v_and_b32_e32 v11, 0xffff0000, v220
	v_add_f32_e32 v240, v240, v11
	v_lshlrev_b32_e32 v10, 16, v221
	v_add_f32_e32 v240, v240, v10
	v_and_b32_e32 v11, 0xffff0000, v221
	v_add_f32_e32 v240, v240, v11
	v_lshlrev_b32_e32 v10, 16, v222
	v_add_f32_e32 v240, v240, v10
	v_and_b32_e32 v11, 0xffff0000, v222
	v_add_f32_e32 v240, v240, v11
	v_lshlrev_b32_e32 v10, 16, v223
	v_add_f32_e32 v240, v240, v10
	v_and_b32_e32 v11, 0xffff0000, v223
	v_add_f32_e32 v240, v240, v11
	v_lshlrev_b32_e32 v10, 16, v224
	v_add_f32_e32 v240, v240, v10
	v_and_b32_e32 v11, 0xffff0000, v224
	v_add_f32_e32 v240, v240, v11
	v_lshlrev_b32_e32 v10, 16, v225
	v_add_f32_e32 v240, v240, v10
	v_and_b32_e32 v11, 0xffff0000, v225
	v_add_f32_e32 v240, v240, v11
	s_waitcnt vmcnt(0)
	v_lshlrev_b32_e32 v10, 16, v226
	v_add_f32_e32 v241, 0, v10
	v_and_b32_e32 v11, 0xffff0000, v226
	v_add_f32_e32 v241, v241, v11
	v_lshlrev_b32_e32 v10, 16, v227
	v_add_f32_e32 v241, v241, v10
	v_and_b32_e32 v11, 0xffff0000, v227
	v_add_f32_e32 v241, v241, v11
	v_lshlrev_b32_e32 v10, 16, v228
	v_add_f32_e32 v241, v241, v10
	v_and_b32_e32 v11, 0xffff0000, v228
	v_add_f32_e32 v241, v241, v11
	v_lshlrev_b32_e32 v10, 16, v229
	v_add_f32_e32 v241, v241, v10
	v_and_b32_e32 v11, 0xffff0000, v229
	v_add_f32_e32 v241, v241, v11
	v_lshlrev_b32_e32 v10, 16, v230
	v_add_f32_e32 v241, v241, v10
	v_and_b32_e32 v11, 0xffff0000, v230
	v_add_f32_e32 v241, v241, v11
	v_lshlrev_b32_e32 v10, 16, v231
	v_add_f32_e32 v241, v241, v10
	v_and_b32_e32 v11, 0xffff0000, v231
	v_add_f32_e32 v241, v241, v11
	v_lshlrev_b32_e32 v10, 16, v232
	v_add_f32_e32 v241, v241, v10
	v_and_b32_e32 v11, 0xffff0000, v232
	v_add_f32_e32 v241, v241, v11
	v_lshlrev_b32_e32 v10, 16, v233
	v_add_f32_e32 v241, v241, v10
	v_and_b32_e32 v11, 0xffff0000, v233
	v_add_f32_e32 v241, v241, v11
	ds_bpermute_b32 v2, v71, v234
	ds_bpermute_b32 v3, v71, v235
	ds_bpermute_b32 v4, v71, v236
	ds_bpermute_b32 v5, v71, v237
	ds_bpermute_b32 v6, v71, v238
	ds_bpermute_b32 v7, v71, v239
	ds_bpermute_b32 v8, v71, v240
	ds_bpermute_b32 v9, v71, v241
	s_waitcnt lgkmcnt(0)
	v_add_f32_e32 v234, v234, v2
	v_add_f32_e32 v235, v235, v3
	v_add_f32_e32 v236, v236, v4
	v_add_f32_e32 v237, v237, v5
	v_add_f32_e32 v238, v238, v6
	v_add_f32_e32 v239, v239, v7
	v_add_f32_e32 v240, v240, v8
	v_add_f32_e32 v241, v241, v9
	ds_bpermute_b32 v2, v72, v234
	ds_bpermute_b32 v3, v72, v235
	ds_bpermute_b32 v4, v72, v236
	ds_bpermute_b32 v5, v72, v237
	ds_bpermute_b32 v6, v72, v238
	ds_bpermute_b32 v7, v72, v239
	ds_bpermute_b32 v8, v72, v240
	ds_bpermute_b32 v9, v72, v241
	s_waitcnt lgkmcnt(0)
	v_add_f32_e32 v234, v234, v2
	v_add_f32_e32 v235, v235, v3
	v_add_f32_e32 v236, v236, v4
	v_add_f32_e32 v237, v237, v5
	v_add_f32_e32 v238, v238, v6
	v_add_f32_e32 v239, v239, v7
	v_add_f32_e32 v240, v240, v8
	v_add_f32_e32 v241, v241, v9
	ds_bpermute_b32 v2, v73, v234
	ds_bpermute_b32 v3, v73, v235
	ds_bpermute_b32 v4, v73, v236
	ds_bpermute_b32 v5, v73, v237
	ds_bpermute_b32 v6, v73, v238
	ds_bpermute_b32 v7, v73, v239
	ds_bpermute_b32 v8, v73, v240
	ds_bpermute_b32 v9, v73, v241
	s_waitcnt lgkmcnt(0)
; __device__ __forceinline__ float wave_sum(float v, int lane) { for (int o = 32; o >= 1; o >>= 1) v += shx(v, o, lane); return v; }
; __device__ __forceinline__ void sg_mfma_phase(int wave_s, const bf16_t* Z, bf16_t* SGO, const float* sgw, const float* sgb, const float* lng, const float* lnb, LAS unsigned char* lds) {
;     ...
;             const float mu = wave_sum(s, lane) * (1.0f / 1024.0f); float q = 0.f;
; #pragma unroll
;             for (int i = 0; i < 16; ++i) { const float dd = f[i] - mu; q += dd * dd; }
	v_add_f32_e32 v234, v234, v2
	v_add_f32_e32 v235, v235, v3
	v_add_f32_e32 v236, v236, v4
	v_add_f32_e32 v237, v237, v5
	v_add_f32_e32 v238, v238, v6
	v_add_f32_e32 v239, v239, v7
	v_add_f32_e32 v240, v240, v8
	v_add_f32_e32 v241, v241, v9
	ds_bpermute_b32 v2, v74, v234
	ds_bpermute_b32 v3, v74, v235
	ds_bpermute_b32 v4, v74, v236
	ds_bpermute_b32 v5, v74, v237
	ds_bpermute_b32 v6, v74, v238
	ds_bpermute_b32 v7, v74, v239
	ds_bpermute_b32 v8, v74, v240
	ds_bpermute_b32 v9, v74, v241
	s_waitcnt lgkmcnt(0)
	v_add_f32_e32 v234, v234, v2
	v_add_f32_e32 v235, v235, v3
	v_add_f32_e32 v236, v236, v4
	v_add_f32_e32 v237, v237, v5
	v_add_f32_e32 v238, v238, v6
	v_add_f32_e32 v239, v239, v7
	v_add_f32_e32 v240, v240, v8
	v_add_f32_e32 v241, v241, v9
	ds_bpermute_b32 v2, v75, v234
	ds_bpermute_b32 v3, v75, v235
	ds_bpermute_b32 v4, v75, v236
	ds_bpermute_b32 v5, v75, v237
	ds_bpermute_b32 v6, v75, v238
	ds_bpermute_b32 v7, v75, v239
	ds_bpermute_b32 v8, v75, v240
	ds_bpermute_b32 v9, v75, v241
	s_waitcnt lgkmcnt(0)
	v_add_f32_e32 v234, v234, v2
	v_add_f32_e32 v235, v235, v3
	v_add_f32_e32 v236, v236, v4
	v_add_f32_e32 v237, v237, v5
	v_add_f32_e32 v238, v238, v6
	v_add_f32_e32 v239, v239, v7
	v_add_f32_e32 v240, v240, v8
	v_add_f32_e32 v241, v241, v9
	ds_bpermute_b32 v2, v76, v234
	ds_bpermute_b32 v3, v76, v235
	ds_bpermute_b32 v4, v76, v236
	ds_bpermute_b32 v5, v76, v237
	ds_bpermute_b32 v6, v76, v238
	ds_bpermute_b32 v7, v76, v239
	ds_bpermute_b32 v8, v76, v240
	ds_bpermute_b32 v9, v76, v241
	s_waitcnt lgkmcnt(0)
	v_add_f32_e32 v234, v234, v2
	v_add_f32_e32 v235, v235, v3
	v_add_f32_e32 v236, v236, v4
	v_add_f32_e32 v237, v237, v5
	v_add_f32_e32 v238, v238, v6
	v_add_f32_e32 v239, v239, v7
	v_add_f32_e32 v240, v240, v8
	v_add_f32_e32 v241, v241, v9
	v_and_b32_e32 v10, 0xffff0000, v170
	v_fmac_f32_e32 v10, 0xba800000, v234
	v_mul_f32_e32 v242, v10, v10
	v_lshlrev_b32_e32 v10, 16, v170
	v_fmac_f32_e32 v10, 0xba800000, v234
	v_fmac_f32_e32 v242, v10, v10
	v_lshlrev_b32_e32 v10, 16, v171
	v_fmac_f32_e32 v10, 0xba800000, v234
	v_fmac_f32_e32 v242, v10, v10
	v_and_b32_e32 v10, 0xffff0000, v171
	v_fmac_f32_e32 v10, 0xba800000, v234
	v_fmac_f32_e32 v242, v10, v10
	v_lshlrev_b32_e32 v10, 16, v172
	v_fmac_f32_e32 v10, 0xba800000, v234
	v_fmac_f32_e32 v242, v10, v10
	v_and_b32_e32 v10, 0xffff0000, v172
	v_fmac_f32_e32 v10, 0xba800000, v234
	v_fmac_f32_e32 v242, v10, v10
	v_lshlrev_b32_e32 v10, 16, v173
	v_fmac_f32_e32 v10, 0xba800000, v234
	v_fmac_f32_e32 v242, v10, v10
	v_and_b32_e32 v10, 0xffff0000, v173
	v_fmac_f32_e32 v10, 0xba800000, v234
	v_fmac_f32_e32 v242, v10, v10
	v_lshlrev_b32_e32 v10, 16, v174
	v_fmac_f32_e32 v10, 0xba800000, v234
	v_fmac_f32_e32 v242, v10, v10
	v_and_b32_e32 v10, 0xffff0000, v174
	v_fmac_f32_e32 v10, 0xba800000, v234
	v_fmac_f32_e32 v242, v10, v10
	v_lshlrev_b32_e32 v10, 16, v175
	v_fmac_f32_e32 v10, 0xba800000, v234
	v_fmac_f32_e32 v242, v10, v10
	v_and_b32_e32 v10, 0xffff0000, v175
	v_fmac_f32_e32 v10, 0xba800000, v234
	v_fmac_f32_e32 v242, v10, v10
	v_lshlrev_b32_e32 v10, 16, v176
	v_fmac_f32_e32 v10, 0xba800000, v234
	v_fmac_f32_e32 v242, v10, v10
	v_and_b32_e32 v10, 0xffff0000, v176
	v_fmac_f32_e32 v10, 0xba800000, v234
	v_fmac_f32_e32 v242, v10, v10
	v_lshlrev_b32_e32 v10, 16, v177
	v_fmac_f32_e32 v10, 0xba800000, v234
	v_fmac_f32_e32 v242, v10, v10
	v_and_b32_e32 v10, 0xffff0000, v177
	v_fmac_f32_e32 v10, 0xba800000, v234
	v_fmac_f32_e32 v242, v10, v10
	v_and_b32_e32 v10, 0xffff0000, v178
	v_fmac_f32_e32 v10, 0xba800000, v235
	v_mul_f32_e32 v243, v10, v10
	v_lshlrev_b32_e32 v10, 16, v178
	v_fmac_f32_e32 v10, 0xba800000, v235
	v_fmac_f32_e32 v243, v10, v10
	v_lshlrev_b32_e32 v10, 16, v179
	v_fmac_f32_e32 v10, 0xba800000, v235
	v_fmac_f32_e32 v243, v10, v10
	v_and_b32_e32 v10, 0xffff0000, v179
	v_fmac_f32_e32 v10, 0xba800000, v235
	v_fmac_f32_e32 v243, v10, v10
	v_lshlrev_b32_e32 v10, 16, v180
	v_fmac_f32_e32 v10, 0xba800000, v235
	v_fmac_f32_e32 v243, v10, v10
	v_and_b32_e32 v10, 0xffff0000, v180
	v_fmac_f32_e32 v10, 0xba800000, v235
	v_fmac_f32_e32 v243, v10, v10
	v_lshlrev_b32_e32 v10, 16, v181
	v_fmac_f32_e32 v10, 0xba800000, v235
	v_fmac_f32_e32 v243, v10, v10
	v_and_b32_e32 v10, 0xffff0000, v181
	v_fmac_f32_e32 v10, 0xba800000, v235
	v_fmac_f32_e32 v243, v10, v10
	v_lshlrev_b32_e32 v10, 16, v182
	v_fmac_f32_e32 v10, 0xba800000, v235
	v_fmac_f32_e32 v243, v10, v10
	v_and_b32_e32 v10, 0xffff0000, v182
	v_fmac_f32_e32 v10, 0xba800000, v235
	v_fmac_f32_e32 v243, v10, v10
	v_lshlrev_b32_e32 v10, 16, v183
	v_fmac_f32_e32 v10, 0xba800000, v235
	v_fmac_f32_e32 v243, v10, v10
	v_and_b32_e32 v10, 0xffff0000, v183
	v_fmac_f32_e32 v10, 0xba800000, v235
	v_fmac_f32_e32 v243, v10, v10
	v_lshlrev_b32_e32 v10, 16, v184
	v_fmac_f32_e32 v10, 0xba800000, v235
	v_fmac_f32_e32 v243, v10, v10
	v_and_b32_e32 v10, 0xffff0000, v184
	v_fmac_f32_e32 v10, 0xba800000, v235
	v_fmac_f32_e32 v243, v10, v10
	v_lshlrev_b32_e32 v10, 16, v185
	v_fmac_f32_e32 v10, 0xba800000, v235
	v_fmac_f32_e32 v243, v10, v10
	v_and_b32_e32 v10, 0xffff0000, v185
	v_fmac_f32_e32 v10, 0xba800000, v235
	v_fmac_f32_e32 v243, v10, v10
	v_and_b32_e32 v10, 0xffff0000, v186
	v_fmac_f32_e32 v10, 0xba800000, v236
	v_mul_f32_e32 v244, v10, v10
	v_lshlrev_b32_e32 v10, 16, v186
	v_fmac_f32_e32 v10, 0xba800000, v236
	v_fmac_f32_e32 v244, v10, v10
	v_lshlrev_b32_e32 v10, 16, v187
	v_fmac_f32_e32 v10, 0xba800000, v236
	v_fmac_f32_e32 v244, v10, v10
	v_and_b32_e32 v10, 0xffff0000, v187
	v_fmac_f32_e32 v10, 0xba800000, v236
	v_fmac_f32_e32 v244, v10, v10
	v_lshlrev_b32_e32 v10, 16, v188
	v_fmac_f32_e32 v10, 0xba800000, v236
	v_fmac_f32_e32 v244, v10, v10
	v_and_b32_e32 v10, 0xffff0000, v188
; __device__ __forceinline__ void sg_mfma_phase(int wave_s, const bf16_t* Z, bf16_t* SGO, const float* sgw, const float* sgb, const float* lng, const float* lnb, LAS unsigned char* lds) {
;     ...
; #pragma unroll
;             for (int i = 0; i < 16; ++i) { const float dd = f[i] - mu; q += dd * dd; }
	v_fmac_f32_e32 v10, 0xba800000, v236
	v_fmac_f32_e32 v244, v10, v10
	v_lshlrev_b32_e32 v10, 16, v189
	v_fmac_f32_e32 v10, 0xba800000, v236
	v_fmac_f32_e32 v244, v10, v10
	v_and_b32_e32 v10, 0xffff0000, v189
	v_fmac_f32_e32 v10, 0xba800000, v236
	v_fmac_f32_e32 v244, v10, v10
	v_lshlrev_b32_e32 v10, 16, v190
	v_fmac_f32_e32 v10, 0xba800000, v236
	v_fmac_f32_e32 v244, v10, v10
	v_and_b32_e32 v10, 0xffff0000, v190
	v_fmac_f32_e32 v10, 0xba800000, v236
	v_fmac_f32_e32 v244, v10, v10
	v_lshlrev_b32_e32 v10, 16, v191
	v_fmac_f32_e32 v10, 0xba800000, v236
	v_fmac_f32_e32 v244, v10, v10
	v_and_b32_e32 v10, 0xffff0000, v191
	v_fmac_f32_e32 v10, 0xba800000, v236
	v_fmac_f32_e32 v244, v10, v10
	v_lshlrev_b32_e32 v10, 16, v192
	v_fmac_f32_e32 v10, 0xba800000, v236
	v_fmac_f32_e32 v244, v10, v10
	v_and_b32_e32 v10, 0xffff0000, v192
	v_fmac_f32_e32 v10, 0xba800000, v236
	v_fmac_f32_e32 v244, v10, v10
	v_lshlrev_b32_e32 v10, 16, v193
	v_fmac_f32_e32 v10, 0xba800000, v236
	v_fmac_f32_e32 v244, v10, v10
	v_and_b32_e32 v10, 0xffff0000, v193
	v_fmac_f32_e32 v10, 0xba800000, v236
	v_fmac_f32_e32 v244, v10, v10
	v_and_b32_e32 v10, 0xffff0000, v194
	v_fmac_f32_e32 v10, 0xba800000, v237
	v_mul_f32_e32 v245, v10, v10
	v_lshlrev_b32_e32 v10, 16, v194
	v_fmac_f32_e32 v10, 0xba800000, v237
	v_fmac_f32_e32 v245, v10, v10
	v_lshlrev_b32_e32 v10, 16, v195
	v_fmac_f32_e32 v10, 0xba800000, v237
	v_fmac_f32_e32 v245, v10, v10
	v_and_b32_e32 v10, 0xffff0000, v195
	v_fmac_f32_e32 v10, 0xba800000, v237
	v_fmac_f32_e32 v245, v10, v10
	v_lshlrev_b32_e32 v10, 16, v196
	v_fmac_f32_e32 v10, 0xba800000, v237
	v_fmac_f32_e32 v245, v10, v10
	v_and_b32_e32 v10, 0xffff0000, v196
	v_fmac_f32_e32 v10, 0xba800000, v237
	v_fmac_f32_e32 v245, v10, v10
	v_lshlrev_b32_e32 v10, 16, v197
	v_fmac_f32_e32 v10, 0xba800000, v237
	v_fmac_f32_e32 v245, v10, v10
	v_and_b32_e32 v10, 0xffff0000, v197
	v_fmac_f32_e32 v10, 0xba800000, v237
	v_fmac_f32_e32 v245, v10, v10
	v_lshlrev_b32_e32 v10, 16, v198
	v_fmac_f32_e32 v10, 0xba800000, v237
	v_fmac_f32_e32 v245, v10, v10
	v_and_b32_e32 v10, 0xffff0000, v198
	v_fmac_f32_e32 v10, 0xba800000, v237
	v_fmac_f32_e32 v245, v10, v10
	v_lshlrev_b32_e32 v10, 16, v199
	v_fmac_f32_e32 v10, 0xba800000, v237
	v_fmac_f32_e32 v245, v10, v10
	v_and_b32_e32 v10, 0xffff0000, v199
	v_fmac_f32_e32 v10, 0xba800000, v237
	v_fmac_f32_e32 v245, v10, v10
	v_lshlrev_b32_e32 v10, 16, v200
	v_fmac_f32_e32 v10, 0xba800000, v237
	v_fmac_f32_e32 v245, v10, v10
	v_and_b32_e32 v10, 0xffff0000, v200
	v_fmac_f32_e32 v10, 0xba800000, v237
	v_fmac_f32_e32 v245, v10, v10
	v_lshlrev_b32_e32 v10, 16, v201
	v_fmac_f32_e32 v10, 0xba800000, v237
	v_fmac_f32_e32 v245, v10, v10
	v_and_b32_e32 v10, 0xffff0000, v201
	v_fmac_f32_e32 v10, 0xba800000, v237
	v_fmac_f32_e32 v245, v10, v10
	v_and_b32_e32 v10, 0xffff0000, v202
	v_fmac_f32_e32 v10, 0xba800000, v238
	v_mul_f32_e32 v246, v10, v10
	v_lshlrev_b32_e32 v10, 16, v202
	v_fmac_f32_e32 v10, 0xba800000, v238
	v_fmac_f32_e32 v246, v10, v10
	v_lshlrev_b32_e32 v10, 16, v203
	v_fmac_f32_e32 v10, 0xba800000, v238
	v_fmac_f32_e32 v246, v10, v10
	v_and_b32_e32 v10, 0xffff0000, v203
	v_fmac_f32_e32 v10, 0xba800000, v238
	v_fmac_f32_e32 v246, v10, v10
	v_lshlrev_b32_e32 v10, 16, v204
	v_fmac_f32_e32 v10, 0xba800000, v238
	v_fmac_f32_e32 v246, v10, v10
	v_and_b32_e32 v10, 0xffff0000, v204
	v_fmac_f32_e32 v10, 0xba800000, v238
	v_fmac_f32_e32 v246, v10, v10
	v_lshlrev_b32_e32 v10, 16, v205
	v_fmac_f32_e32 v10, 0xba800000, v238
	v_fmac_f32_e32 v246, v10, v10
	v_and_b32_e32 v10, 0xffff0000, v205
	v_fmac_f32_e32 v10, 0xba800000, v238
	v_fmac_f32_e32 v246, v10, v10
	v_lshlrev_b32_e32 v10, 16, v206
	v_fmac_f32_e32 v10, 0xba800000, v238
	v_fmac_f32_e32 v246, v10, v10
	v_and_b32_e32 v10, 0xffff0000, v206
	v_fmac_f32_e32 v10, 0xba800000, v238
	v_fmac_f32_e32 v246, v10, v10
	v_lshlrev_b32_e32 v10, 16, v207
	v_fmac_f32_e32 v10, 0xba800000, v238
	v_fmac_f32_e32 v246, v10, v10
	v_and_b32_e32 v10, 0xffff0000, v207
	v_fmac_f32_e32 v10, 0xba800000, v238
	v_fmac_f32_e32 v246, v10, v10
	v_lshlrev_b32_e32 v10, 16, v208
	v_fmac_f32_e32 v10, 0xba800000, v238
	v_fmac_f32_e32 v246, v10, v10
	v_and_b32_e32 v10, 0xffff0000, v208
	v_fmac_f32_e32 v10, 0xba800000, v238
	v_fmac_f32_e32 v246, v10, v10
	v_lshlrev_b32_e32 v10, 16, v209
	v_fmac_f32_e32 v10, 0xba800000, v238
	v_fmac_f32_e32 v246, v10, v10
	v_and_b32_e32 v10, 0xffff0000, v209
	v_fmac_f32_e32 v10, 0xba800000, v238
	v_fmac_f32_e32 v246, v10, v10
	v_and_b32_e32 v10, 0xffff0000, v210
	v_fmac_f32_e32 v10, 0xba800000, v239
	v_mul_f32_e32 v247, v10, v10
	v_lshlrev_b32_e32 v10, 16, v210
	v_fmac_f32_e32 v10, 0xba800000, v239
	v_fmac_f32_e32 v247, v10, v10
	v_lshlrev_b32_e32 v10, 16, v211
	v_fmac_f32_e32 v10, 0xba800000, v239
	v_fmac_f32_e32 v247, v10, v10
	v_and_b32_e32 v10, 0xffff0000, v211
	v_fmac_f32_e32 v10, 0xba800000, v239
	v_fmac_f32_e32 v247, v10, v10
	v_lshlrev_b32_e32 v10, 16, v212
	v_fmac_f32_e32 v10, 0xba800000, v239
	v_fmac_f32_e32 v247, v10, v10
	v_and_b32_e32 v10, 0xffff0000, v212
	v_fmac_f32_e32 v10, 0xba800000, v239
	v_fmac_f32_e32 v247, v10, v10
	v_lshlrev_b32_e32 v10, 16, v213
	v_fmac_f32_e32 v10, 0xba800000, v239
	v_fmac_f32_e32 v247, v10, v10
	v_and_b32_e32 v10, 0xffff0000, v213
	v_fmac_f32_e32 v10, 0xba800000, v239
	v_fmac_f32_e32 v247, v10, v10
	v_lshlrev_b32_e32 v10, 16, v214
	v_fmac_f32_e32 v10, 0xba800000, v239
	v_fmac_f32_e32 v247, v10, v10
	v_and_b32_e32 v10, 0xffff0000, v214
	v_fmac_f32_e32 v10, 0xba800000, v239
	v_fmac_f32_e32 v247, v10, v10
	v_lshlrev_b32_e32 v10, 16, v215
	v_fmac_f32_e32 v10, 0xba800000, v239
	v_fmac_f32_e32 v247, v10, v10
	v_and_b32_e32 v10, 0xffff0000, v215
	v_fmac_f32_e32 v10, 0xba800000, v239
; __device__ __forceinline__ float wave_sum(float v, int lane) { for (int o = 32; o >= 1; o >>= 1) v += shx(v, o, lane); return v; }
; __device__ __forceinline__ void sg_mfma_phase(int wave_s, const bf16_t* Z, bf16_t* SGO, const float* sgw, const float* sgb, const float* lng, const float* lnb, LAS unsigned char* lds) {
;     ...
;             for (int i = 0; i < 16; ++i) { const float dd = f[i] - mu; q += dd * dd; }
;             q = wave_sum(q, lane);
	v_fmac_f32_e32 v247, v10, v10
	v_lshlrev_b32_e32 v10, 16, v216
	v_fmac_f32_e32 v10, 0xba800000, v239
	v_fmac_f32_e32 v247, v10, v10
	v_and_b32_e32 v10, 0xffff0000, v216
	v_fmac_f32_e32 v10, 0xba800000, v239
	v_fmac_f32_e32 v247, v10, v10
	v_lshlrev_b32_e32 v10, 16, v217
	v_fmac_f32_e32 v10, 0xba800000, v239
	v_fmac_f32_e32 v247, v10, v10
	v_and_b32_e32 v10, 0xffff0000, v217
	v_fmac_f32_e32 v10, 0xba800000, v239
	v_fmac_f32_e32 v247, v10, v10
	v_and_b32_e32 v10, 0xffff0000, v218
	v_fmac_f32_e32 v10, 0xba800000, v240
	v_mul_f32_e32 v248, v10, v10
	v_lshlrev_b32_e32 v10, 16, v218
	v_fmac_f32_e32 v10, 0xba800000, v240
	v_fmac_f32_e32 v248, v10, v10
	v_lshlrev_b32_e32 v10, 16, v219
	v_fmac_f32_e32 v10, 0xba800000, v240
	v_fmac_f32_e32 v248, v10, v10
	v_and_b32_e32 v10, 0xffff0000, v219
	v_fmac_f32_e32 v10, 0xba800000, v240
	v_fmac_f32_e32 v248, v10, v10
	v_lshlrev_b32_e32 v10, 16, v220
	v_fmac_f32_e32 v10, 0xba800000, v240
	v_fmac_f32_e32 v248, v10, v10
	v_and_b32_e32 v10, 0xffff0000, v220
	v_fmac_f32_e32 v10, 0xba800000, v240
	v_fmac_f32_e32 v248, v10, v10
	v_lshlrev_b32_e32 v10, 16, v221
	v_fmac_f32_e32 v10, 0xba800000, v240
	v_fmac_f32_e32 v248, v10, v10
	v_and_b32_e32 v10, 0xffff0000, v221
	v_fmac_f32_e32 v10, 0xba800000, v240
	v_fmac_f32_e32 v248, v10, v10
	v_lshlrev_b32_e32 v10, 16, v222
	v_fmac_f32_e32 v10, 0xba800000, v240
	v_fmac_f32_e32 v248, v10, v10
	v_and_b32_e32 v10, 0xffff0000, v222
	v_fmac_f32_e32 v10, 0xba800000, v240
	v_fmac_f32_e32 v248, v10, v10
	v_lshlrev_b32_e32 v10, 16, v223
	v_fmac_f32_e32 v10, 0xba800000, v240
	v_fmac_f32_e32 v248, v10, v10
	v_and_b32_e32 v10, 0xffff0000, v223
	v_fmac_f32_e32 v10, 0xba800000, v240
	v_fmac_f32_e32 v248, v10, v10
	v_lshlrev_b32_e32 v10, 16, v224
	v_fmac_f32_e32 v10, 0xba800000, v240
	v_fmac_f32_e32 v248, v10, v10
	v_and_b32_e32 v10, 0xffff0000, v224
	v_fmac_f32_e32 v10, 0xba800000, v240
	v_fmac_f32_e32 v248, v10, v10
	v_lshlrev_b32_e32 v10, 16, v225
	v_fmac_f32_e32 v10, 0xba800000, v240
	v_fmac_f32_e32 v248, v10, v10
	v_and_b32_e32 v10, 0xffff0000, v225
	v_fmac_f32_e32 v10, 0xba800000, v240
	v_fmac_f32_e32 v248, v10, v10
	v_and_b32_e32 v10, 0xffff0000, v226
	v_fmac_f32_e32 v10, 0xba800000, v241
	v_mul_f32_e32 v249, v10, v10
	v_lshlrev_b32_e32 v10, 16, v226
	v_fmac_f32_e32 v10, 0xba800000, v241
	v_fmac_f32_e32 v249, v10, v10
	v_lshlrev_b32_e32 v10, 16, v227
	v_fmac_f32_e32 v10, 0xba800000, v241
	v_fmac_f32_e32 v249, v10, v10
	v_and_b32_e32 v10, 0xffff0000, v227
	v_fmac_f32_e32 v10, 0xba800000, v241
	v_fmac_f32_e32 v249, v10, v10
	v_lshlrev_b32_e32 v10, 16, v228
	v_fmac_f32_e32 v10, 0xba800000, v241
	v_fmac_f32_e32 v249, v10, v10
	v_and_b32_e32 v10, 0xffff0000, v228
	v_fmac_f32_e32 v10, 0xba800000, v241
	v_fmac_f32_e32 v249, v10, v10
	v_lshlrev_b32_e32 v10, 16, v229
	v_fmac_f32_e32 v10, 0xba800000, v241
	v_fmac_f32_e32 v249, v10, v10
	v_and_b32_e32 v10, 0xffff0000, v229
	v_fmac_f32_e32 v10, 0xba800000, v241
	v_fmac_f32_e32 v249, v10, v10
	v_lshlrev_b32_e32 v10, 16, v230
	v_fmac_f32_e32 v10, 0xba800000, v241
	v_fmac_f32_e32 v249, v10, v10
	v_and_b32_e32 v10, 0xffff0000, v230
	v_fmac_f32_e32 v10, 0xba800000, v241
	v_fmac_f32_e32 v249, v10, v10
	v_lshlrev_b32_e32 v10, 16, v231
	v_fmac_f32_e32 v10, 0xba800000, v241
	v_fmac_f32_e32 v249, v10, v10
	v_and_b32_e32 v10, 0xffff0000, v231
	v_fmac_f32_e32 v10, 0xba800000, v241
	v_fmac_f32_e32 v249, v10, v10
	v_lshlrev_b32_e32 v10, 16, v232
	v_fmac_f32_e32 v10, 0xba800000, v241
	v_fmac_f32_e32 v249, v10, v10
	v_and_b32_e32 v10, 0xffff0000, v232
	v_fmac_f32_e32 v10, 0xba800000, v241
	v_fmac_f32_e32 v249, v10, v10
	v_lshlrev_b32_e32 v10, 16, v233
	v_fmac_f32_e32 v10, 0xba800000, v241
	v_fmac_f32_e32 v249, v10, v10
	v_and_b32_e32 v10, 0xffff0000, v233
	v_fmac_f32_e32 v10, 0xba800000, v241
	v_fmac_f32_e32 v249, v10, v10
	ds_bpermute_b32 v2, v71, v242
	ds_bpermute_b32 v3, v71, v243
	ds_bpermute_b32 v4, v71, v244
	ds_bpermute_b32 v5, v71, v245
	ds_bpermute_b32 v6, v71, v246
	ds_bpermute_b32 v7, v71, v247
	ds_bpermute_b32 v8, v71, v248
	ds_bpermute_b32 v9, v71, v249
	s_waitcnt lgkmcnt(0)
	v_add_f32_e32 v242, v242, v2
	v_add_f32_e32 v243, v243, v3
	v_add_f32_e32 v244, v244, v4
	v_add_f32_e32 v245, v245, v5
	v_add_f32_e32 v246, v246, v6
	v_add_f32_e32 v247, v247, v7
	v_add_f32_e32 v248, v248, v8
	v_add_f32_e32 v249, v249, v9
	ds_bpermute_b32 v2, v72, v242
	ds_bpermute_b32 v3, v72, v243
	ds_bpermute_b32 v4, v72, v244
	ds_bpermute_b32 v5, v72, v245
	ds_bpermute_b32 v6, v72, v246
	ds_bpermute_b32 v7, v72, v247
	ds_bpermute_b32 v8, v72, v248
	ds_bpermute_b32 v9, v72, v249
	s_waitcnt lgkmcnt(0)
	v_add_f32_e32 v242, v242, v2
	v_add_f32_e32 v243, v243, v3
	v_add_f32_e32 v244, v244, v4
	v_add_f32_e32 v245, v245, v5
	v_add_f32_e32 v246, v246, v6
	v_add_f32_e32 v247, v247, v7
	v_add_f32_e32 v248, v248, v8
	v_add_f32_e32 v249, v249, v9
	ds_bpermute_b32 v2, v73, v242
	ds_bpermute_b32 v3, v73, v243
	ds_bpermute_b32 v4, v73, v244
	ds_bpermute_b32 v5, v73, v245
	ds_bpermute_b32 v6, v73, v246
	ds_bpermute_b32 v7, v73, v247
	ds_bpermute_b32 v8, v73, v248
	ds_bpermute_b32 v9, v73, v249
	s_waitcnt lgkmcnt(0)
	v_add_f32_e32 v242, v242, v2
	v_add_f32_e32 v243, v243, v3
	v_add_f32_e32 v244, v244, v4
	v_add_f32_e32 v245, v245, v5
	v_add_f32_e32 v246, v246, v6
	v_add_f32_e32 v247, v247, v7
	v_add_f32_e32 v248, v248, v8
	v_add_f32_e32 v249, v249, v9
	ds_bpermute_b32 v2, v74, v242
	ds_bpermute_b32 v3, v74, v243
	ds_bpermute_b32 v4, v74, v244
	ds_bpermute_b32 v5, v74, v245
	ds_bpermute_b32 v6, v74, v246
	ds_bpermute_b32 v7, v74, v247
	ds_bpermute_b32 v8, v74, v248
	ds_bpermute_b32 v9, v74, v249
	s_waitcnt lgkmcnt(0)
; __device__ __forceinline__ float wave_sum(float v, int lane) { for (int o = 32; o >= 1; o >>= 1) v += shx(v, o, lane); return v; }
; __device__ __forceinline__ void sg_mfma_phase(int wave_s, const bf16_t* Z, bf16_t* SGO, const float* sgw, const float* sgb, const float* lng, const float* lnb, LAS unsigned char* lds) {
;     ...
;             q = wave_sum(q, lane);
;             if (lane == 0) { st[2 * j] = mu; st[2 * j + 1] = 1.0f / sqrtf(q * (1.0f / 1024.0f) + 1e-6f); } }
	v_add_f32_e32 v242, v242, v2
	v_add_f32_e32 v243, v243, v3
	v_add_f32_e32 v244, v244, v4
	v_add_f32_e32 v245, v245, v5
	v_add_f32_e32 v246, v246, v6
	v_add_f32_e32 v247, v247, v7
	v_add_f32_e32 v248, v248, v8
	v_add_f32_e32 v249, v249, v9
	ds_bpermute_b32 v2, v75, v242
	ds_bpermute_b32 v3, v75, v243
	ds_bpermute_b32 v4, v75, v244
	ds_bpermute_b32 v5, v75, v245
	ds_bpermute_b32 v6, v75, v246
	ds_bpermute_b32 v7, v75, v247
	ds_bpermute_b32 v8, v75, v248
	ds_bpermute_b32 v9, v75, v249
	s_waitcnt lgkmcnt(0)
	v_add_f32_e32 v242, v242, v2
	v_add_f32_e32 v243, v243, v3
	v_add_f32_e32 v244, v244, v4
	v_add_f32_e32 v245, v245, v5
	v_add_f32_e32 v246, v246, v6
	v_add_f32_e32 v247, v247, v7
	v_add_f32_e32 v248, v248, v8
	v_add_f32_e32 v249, v249, v9
	ds_bpermute_b32 v2, v76, v242
	ds_bpermute_b32 v3, v76, v243
	ds_bpermute_b32 v4, v76, v244
	ds_bpermute_b32 v5, v76, v245
	ds_bpermute_b32 v6, v76, v246
	ds_bpermute_b32 v7, v76, v247
	ds_bpermute_b32 v8, v76, v248
	ds_bpermute_b32 v9, v76, v249
	s_waitcnt lgkmcnt(0)
	v_add_f32_e32 v242, v242, v2
	v_add_f32_e32 v243, v243, v3
	v_add_f32_e32 v244, v244, v4
	v_add_f32_e32 v245, v245, v5
	v_add_f32_e32 v246, v246, v6
	v_add_f32_e32 v247, v247, v7
	v_add_f32_e32 v248, v248, v8
	v_add_f32_e32 v249, v249, v9
	s_and_saveexec_b64 s[16:17], s[6:7]
	v_mov_b32_e32 v2, v234
	v_mov_b32_e32 v3, v242
	v_fmamk_f32 v3, v3, 0x3a800000, v164
	v_mul_f32_e32 v4, 0x4f800000, v3
	v_cmp_gt_f32_e32 vcc, s18, v3
	v_mul_f32_e32 v2, 0x3a800000, v2
	s_nop 0
	v_cndmask_b32_e32 v3, v3, v4, vcc
	v_sqrt_f32_e32 v4, v3
	s_nop 0
	v_add_u32_e32 v5, -1, v4
	v_fma_f32 v7, -v5, v4, v3
	v_add_u32_e32 v6, 1, v4
	v_cmp_ge_f32_e64 s[10:11], 0, v7
	s_nop 1
	v_cndmask_b32_e64 v5, v4, v5, s[10:11]
	v_fma_f32 v4, -v6, v4, v3
	v_cmp_lt_f32_e64 s[10:11], 0, v4
	s_nop 1
	v_cndmask_b32_e64 v4, v5, v6, s[10:11]
	v_mul_f32_e32 v5, 0x37800000, v4
	v_cndmask_b32_e32 v4, v4, v5, vcc
	v_cmp_class_f32_e32 vcc, v3, v165
	v_add_u32_e32 v6, 0x0, v77
	s_nop 0
	v_cndmask_b32_e32 v3, v4, v3, vcc
	v_div_scale_f32 v4, s[10:11], v3, v3, 1.0
	v_rcp_f32_e32 v5, v4
	s_nop 0
	v_fma_f32 v7, -v4, v5, 1.0
	v_fmac_f32_e32 v5, v7, v5
	v_div_scale_f32 v7, vcc, 1.0, v3, 1.0
	v_mul_f32_e32 v8, v7, v5
	v_fma_f32 v9, -v4, v8, v7
	v_fmac_f32_e32 v8, v9, v5
	v_fma_f32 v4, -v4, v8, v7
	v_div_fmas_f32 v4, v4, v5, v8
	v_div_fixup_f32 v3, v4, v3, 1.0
	ds_write_b64 v6, v[2:3]
	v_mov_b32_e32 v2, v235
	v_mov_b32_e32 v3, v243
	v_fmamk_f32 v3, v3, 0x3a800000, v164
	v_mul_f32_e32 v4, 0x4f800000, v3
	v_cmp_gt_f32_e32 vcc, s18, v3
	v_mul_f32_e32 v2, 0x3a800000, v2
	s_nop 0
	v_cndmask_b32_e32 v3, v3, v4, vcc
	v_sqrt_f32_e32 v4, v3
	s_nop 0
	v_add_u32_e32 v5, -1, v4
	v_fma_f32 v7, -v5, v4, v3
	v_add_u32_e32 v6, 1, v4
	v_cmp_ge_f32_e64 s[10:11], 0, v7
	s_nop 1
	v_cndmask_b32_e64 v5, v4, v5, s[10:11]
	v_fma_f32 v4, -v6, v4, v3
	v_cmp_lt_f32_e64 s[10:11], 0, v4
	s_nop 1
	v_cndmask_b32_e64 v4, v5, v6, s[10:11]
	v_mul_f32_e32 v5, 0x37800000, v4
	v_cndmask_b32_e32 v4, v4, v5, vcc
	v_cmp_class_f32_e32 vcc, v3, v165
	v_add_u32_e32 v6, 0x8, v77
	s_nop 0
	v_cndmask_b32_e32 v3, v4, v3, vcc
	v_div_scale_f32 v4, s[10:11], v3, v3, 1.0
	v_rcp_f32_e32 v5, v4
	s_nop 0
	v_fma_f32 v7, -v4, v5, 1.0
	v_fmac_f32_e32 v5, v7, v5
	v_div_scale_f32 v7, vcc, 1.0, v3, 1.0
	v_mul_f32_e32 v8, v7, v5
	v_fma_f32 v9, -v4, v8, v7
	v_fmac_f32_e32 v8, v9, v5
	v_fma_f32 v4, -v4, v8, v7
	v_div_fmas_f32 v4, v4, v5, v8
	v_div_fixup_f32 v3, v4, v3, 1.0
	ds_write_b64 v6, v[2:3]
	v_mov_b32_e32 v2, v236
	v_mov_b32_e32 v3, v244
	v_fmamk_f32 v3, v3, 0x3a800000, v164
	v_mul_f32_e32 v4, 0x4f800000, v3
	v_cmp_gt_f32_e32 vcc, s18, v3
	v_mul_f32_e32 v2, 0x3a800000, v2
	s_nop 0
	v_cndmask_b32_e32 v3, v3, v4, vcc
	v_sqrt_f32_e32 v4, v3
	s_nop 0
	v_add_u32_e32 v5, -1, v4
	v_fma_f32 v7, -v5, v4, v3
	v_add_u32_e32 v6, 1, v4
	v_cmp_ge_f32_e64 s[10:11], 0, v7
	s_nop 1
	v_cndmask_b32_e64 v5, v4, v5, s[10:11]
	v_fma_f32 v4, -v6, v4, v3
	v_cmp_lt_f32_e64 s[10:11], 0, v4
	s_nop 1
	v_cndmask_b32_e64 v4, v5, v6, s[10:11]
	v_mul_f32_e32 v5, 0x37800000, v4
	v_cndmask_b32_e32 v4, v4, v5, vcc
	v_cmp_class_f32_e32 vcc, v3, v165
	v_add_u32_e32 v6, 0x10, v77
	s_nop 0
	v_cndmask_b32_e32 v3, v4, v3, vcc
	v_div_scale_f32 v4, s[10:11], v3, v3, 1.0
	v_rcp_f32_e32 v5, v4
	s_nop 0
	v_fma_f32 v7, -v4, v5, 1.0
	v_fmac_f32_e32 v5, v7, v5
	v_div_scale_f32 v7, vcc, 1.0, v3, 1.0
	v_mul_f32_e32 v8, v7, v5
	v_fma_f32 v9, -v4, v8, v7
	v_fmac_f32_e32 v8, v9, v5
	v_fma_f32 v4, -v4, v8, v7
	v_div_fmas_f32 v4, v4, v5, v8
	v_div_fixup_f32 v3, v4, v3, 1.0
	ds_write_b64 v6, v[2:3]
	v_mov_b32_e32 v2, v237
	v_mov_b32_e32 v3, v245
	v_fmamk_f32 v3, v3, 0x3a800000, v164
	v_mul_f32_e32 v4, 0x4f800000, v3
	v_cmp_gt_f32_e32 vcc, s18, v3
	v_mul_f32_e32 v2, 0x3a800000, v2
	s_nop 0
	v_cndmask_b32_e32 v3, v3, v4, vcc
	v_sqrt_f32_e32 v4, v3
	s_nop 0
	v_add_u32_e32 v5, -1, v4
	v_fma_f32 v7, -v5, v4, v3
	v_add_u32_e32 v6, 1, v4
	v_cmp_ge_f32_e64 s[10:11], 0, v7
	s_nop 1
	v_cndmask_b32_e64 v5, v4, v5, s[10:11]
	v_fma_f32 v4, -v6, v4, v3
	v_cmp_lt_f32_e64 s[10:11], 0, v4
	s_nop 1
	v_cndmask_b32_e64 v4, v5, v6, s[10:11]
	v_mul_f32_e32 v5, 0x37800000, v4
	v_cndmask_b32_e32 v4, v4, v5, vcc
	v_cmp_class_f32_e32 vcc, v3, v165
	v_add_u32_e32 v6, 0x18, v77
	s_nop 0
	v_cndmask_b32_e32 v3, v4, v3, vcc
	v_div_scale_f32 v4, s[10:11], v3, v3, 1.0
	v_rcp_f32_e32 v5, v4
	s_nop 0
	v_fma_f32 v7, -v4, v5, 1.0
	v_fmac_f32_e32 v5, v7, v5
	v_div_scale_f32 v7, vcc, 1.0, v3, 1.0
	v_mul_f32_e32 v8, v7, v5
	v_fma_f32 v9, -v4, v8, v7
	v_fmac_f32_e32 v8, v9, v5
	v_fma_f32 v4, -v4, v8, v7
	v_div_fmas_f32 v4, v4, v5, v8
	v_div_fixup_f32 v3, v4, v3, 1.0
	ds_write_b64 v6, v[2:3]
	v_mov_b32_e32 v2, v238
	v_mov_b32_e32 v3, v246
; __device__ __forceinline__ void sg_mfma_phase(int wave_s, const bf16_t* Z, bf16_t* SGO, const float* sgw, const float* sgb, const float* lng, const float* lnb, LAS unsigned char* lds) {
;     ...
;         for (int rr = 0; rr < 16; ++rr) { const int j = wave * 16 + rr; const bf16_t* vp = Z + (row0 + j) * N1 + 5632 + lane * 16;
;             const u32x4 a = *(const u32x4*)vp, b = *(const u32x4*)(vp + 8); float f[16];
;     ...
;             if (lane == 0) { st[2 * j] = mu; st[2 * j + 1] = 1.0f / sqrtf(q * (1.0f / 1024.0f) + 1e-6f); } }
	v_fmamk_f32 v3, v3, 0x3a800000, v164
	v_mul_f32_e32 v4, 0x4f800000, v3
	v_cmp_gt_f32_e32 vcc, s18, v3
	v_mul_f32_e32 v2, 0x3a800000, v2
	s_nop 0
	v_cndmask_b32_e32 v3, v3, v4, vcc
	v_sqrt_f32_e32 v4, v3
	s_nop 0
	v_add_u32_e32 v5, -1, v4
	v_fma_f32 v7, -v5, v4, v3
	v_add_u32_e32 v6, 1, v4
	v_cmp_ge_f32_e64 s[10:11], 0, v7
	s_nop 1
	v_cndmask_b32_e64 v5, v4, v5, s[10:11]
	v_fma_f32 v4, -v6, v4, v3
	v_cmp_lt_f32_e64 s[10:11], 0, v4
	s_nop 1
	v_cndmask_b32_e64 v4, v5, v6, s[10:11]
	v_mul_f32_e32 v5, 0x37800000, v4
	v_cndmask_b32_e32 v4, v4, v5, vcc
	v_cmp_class_f32_e32 vcc, v3, v165
	v_add_u32_e32 v6, 0x20, v77
	s_nop 0
	v_cndmask_b32_e32 v3, v4, v3, vcc
	v_div_scale_f32 v4, s[10:11], v3, v3, 1.0
	v_rcp_f32_e32 v5, v4
	s_nop 0
	v_fma_f32 v7, -v4, v5, 1.0
	v_fmac_f32_e32 v5, v7, v5
	v_div_scale_f32 v7, vcc, 1.0, v3, 1.0
	v_mul_f32_e32 v8, v7, v5
	v_fma_f32 v9, -v4, v8, v7
	v_fmac_f32_e32 v8, v9, v5
	v_fma_f32 v4, -v4, v8, v7
	v_div_fmas_f32 v4, v4, v5, v8
	v_div_fixup_f32 v3, v4, v3, 1.0
	ds_write_b64 v6, v[2:3]
	v_mov_b32_e32 v2, v239
	v_mov_b32_e32 v3, v247
	v_fmamk_f32 v3, v3, 0x3a800000, v164
	v_mul_f32_e32 v4, 0x4f800000, v3
	v_cmp_gt_f32_e32 vcc, s18, v3
	v_mul_f32_e32 v2, 0x3a800000, v2
	s_nop 0
	v_cndmask_b32_e32 v3, v3, v4, vcc
	v_sqrt_f32_e32 v4, v3
	s_nop 0
	v_add_u32_e32 v5, -1, v4
	v_fma_f32 v7, -v5, v4, v3
	v_add_u32_e32 v6, 1, v4
	v_cmp_ge_f32_e64 s[10:11], 0, v7
	s_nop 1
	v_cndmask_b32_e64 v5, v4, v5, s[10:11]
	v_fma_f32 v4, -v6, v4, v3
	v_cmp_lt_f32_e64 s[10:11], 0, v4
	s_nop 1
	v_cndmask_b32_e64 v4, v5, v6, s[10:11]
	v_mul_f32_e32 v5, 0x37800000, v4
	v_cndmask_b32_e32 v4, v4, v5, vcc
	v_cmp_class_f32_e32 vcc, v3, v165
	v_add_u32_e32 v6, 0x28, v77
	s_nop 0
	v_cndmask_b32_e32 v3, v4, v3, vcc
	v_div_scale_f32 v4, s[10:11], v3, v3, 1.0
	v_rcp_f32_e32 v5, v4
	s_nop 0
	v_fma_f32 v7, -v4, v5, 1.0
	v_fmac_f32_e32 v5, v7, v5
	v_div_scale_f32 v7, vcc, 1.0, v3, 1.0
	v_mul_f32_e32 v8, v7, v5
	v_fma_f32 v9, -v4, v8, v7
	v_fmac_f32_e32 v8, v9, v5
	v_fma_f32 v4, -v4, v8, v7
	v_div_fmas_f32 v4, v4, v5, v8
	v_div_fixup_f32 v3, v4, v3, 1.0
	ds_write_b64 v6, v[2:3]
	v_mov_b32_e32 v2, v240
	v_mov_b32_e32 v3, v248
	v_fmamk_f32 v3, v3, 0x3a800000, v164
	v_mul_f32_e32 v4, 0x4f800000, v3
	v_cmp_gt_f32_e32 vcc, s18, v3
	v_mul_f32_e32 v2, 0x3a800000, v2
	s_nop 0
	v_cndmask_b32_e32 v3, v3, v4, vcc
	v_sqrt_f32_e32 v4, v3
	s_nop 0
	v_add_u32_e32 v5, -1, v4
	v_fma_f32 v7, -v5, v4, v3
	v_add_u32_e32 v6, 1, v4
	v_cmp_ge_f32_e64 s[10:11], 0, v7
	s_nop 1
	v_cndmask_b32_e64 v5, v4, v5, s[10:11]
	v_fma_f32 v4, -v6, v4, v3
	v_cmp_lt_f32_e64 s[10:11], 0, v4
	s_nop 1
	v_cndmask_b32_e64 v4, v5, v6, s[10:11]
	v_mul_f32_e32 v5, 0x37800000, v4
	v_cndmask_b32_e32 v4, v4, v5, vcc
	v_cmp_class_f32_e32 vcc, v3, v165
	v_add_u32_e32 v6, 0x30, v77
	s_nop 0
	v_cndmask_b32_e32 v3, v4, v3, vcc
	v_div_scale_f32 v4, s[10:11], v3, v3, 1.0
	v_rcp_f32_e32 v5, v4
	s_nop 0
	v_fma_f32 v7, -v4, v5, 1.0
	v_fmac_f32_e32 v5, v7, v5
	v_div_scale_f32 v7, vcc, 1.0, v3, 1.0
	v_mul_f32_e32 v8, v7, v5
	v_fma_f32 v9, -v4, v8, v7
	v_fmac_f32_e32 v8, v9, v5
	v_fma_f32 v4, -v4, v8, v7
	v_div_fmas_f32 v4, v4, v5, v8
	v_div_fixup_f32 v3, v4, v3, 1.0
	ds_write_b64 v6, v[2:3]
	v_mov_b32_e32 v2, v241
	v_mov_b32_e32 v3, v249
	v_fmamk_f32 v3, v3, 0x3a800000, v164
	v_mul_f32_e32 v4, 0x4f800000, v3
	v_cmp_gt_f32_e32 vcc, s18, v3
	v_mul_f32_e32 v2, 0x3a800000, v2
	s_nop 0
	v_cndmask_b32_e32 v3, v3, v4, vcc
	v_sqrt_f32_e32 v4, v3
	s_nop 0
	v_add_u32_e32 v5, -1, v4
	v_fma_f32 v7, -v5, v4, v3
	v_add_u32_e32 v6, 1, v4
	v_cmp_ge_f32_e64 s[10:11], 0, v7
	s_nop 1
	v_cndmask_b32_e64 v5, v4, v5, s[10:11]
	v_fma_f32 v4, -v6, v4, v3
	v_cmp_lt_f32_e64 s[10:11], 0, v4
	s_nop 1
	v_cndmask_b32_e64 v4, v5, v6, s[10:11]
	v_mul_f32_e32 v5, 0x37800000, v4
	v_cndmask_b32_e32 v4, v4, v5, vcc
	v_cmp_class_f32_e32 vcc, v3, v165
	v_add_u32_e32 v6, 0x38, v77
	s_nop 0
	v_cndmask_b32_e32 v3, v4, v3, vcc
	v_div_scale_f32 v4, s[10:11], v3, v3, 1.0
	v_rcp_f32_e32 v5, v4
	s_nop 0
	v_fma_f32 v7, -v4, v5, 1.0
	v_fmac_f32_e32 v5, v7, v5
	v_div_scale_f32 v7, vcc, 1.0, v3, 1.0
	v_mul_f32_e32 v8, v7, v5
	v_fma_f32 v9, -v4, v8, v7
	v_fmac_f32_e32 v8, v9, v5
	v_fma_f32 v4, -v4, v8, v7
	v_div_fmas_f32 v4, v4, v5, v8
	v_div_fixup_f32 v3, v4, v3, 1.0
	ds_write_b64 v6, v[2:3]
	s_or_b64 exec, exec, s[16:17]
	s_mov_b64 s[10:11], 0x3400
	global_load_dwordx4 v[170:173], v[0:1], off
	global_load_dwordx4 v[174:177], v[0:1], off offset:16
	v_lshl_add_u64 v[0:1], v[0:1], 0, s[10:11]
	global_load_dwordx4 v[178:181], v[0:1], off
	global_load_dwordx4 v[182:185], v[0:1], off offset:16
	v_lshl_add_u64 v[0:1], v[0:1], 0, s[10:11]
	global_load_dwordx4 v[186:189], v[0:1], off
	global_load_dwordx4 v[190:193], v[0:1], off offset:16
	v_lshl_add_u64 v[0:1], v[0:1], 0, s[10:11]
	global_load_dwordx4 v[194:197], v[0:1], off
	global_load_dwordx4 v[198:201], v[0:1], off offset:16
	v_lshl_add_u64 v[0:1], v[0:1], 0, s[10:11]
	global_load_dwordx4 v[202:205], v[0:1], off
	global_load_dwordx4 v[206:209], v[0:1], off offset:16
	v_lshl_add_u64 v[0:1], v[0:1], 0, s[10:11]
	global_load_dwordx4 v[210:213], v[0:1], off
	global_load_dwordx4 v[214:217], v[0:1], off offset:16
	v_lshl_add_u64 v[0:1], v[0:1], 0, s[10:11]
	global_load_dwordx4 v[218:221], v[0:1], off
	global_load_dwordx4 v[222:225], v[0:1], off offset:16
	v_lshl_add_u64 v[0:1], v[0:1], 0, s[10:11]
	global_load_dwordx4 v[226:229], v[0:1], off
	global_load_dwordx4 v[230:233], v[0:1], off offset:16
	v_lshl_add_u64 v[0:1], v[0:1], 0, s[10:11]
	s_waitcnt vmcnt(14)
; __device__ __forceinline__ float bflo(unsigned w) { return __uint_as_float(w << 16); }
; __device__ __forceinline__ float bfhi(unsigned w) { return __uint_as_float(w & 0xffff0000u); }
; __device__ __forceinline__ void sg_mfma_phase(int wave_s, const bf16_t* Z, bf16_t* SGO, const float* sgw, const float* sgb, const float* lng, const float* lnb, LAS unsigned char* lds) {
;     ...
;         for (int rr = 0; rr < 16; ++rr) { const int j = wave * 16 + rr; const bf16_t* vp = Z + (row0 + j) * N1 + 5632 + lane * 16;
;             const u32x4 a = *(const u32x4*)vp, b = *(const u32x4*)(vp + 8); float f[16];
;             f[0] = bflo(a.x); f[1] = bfhi(a.x); f[2] = bflo(a.y); f[3] = bfhi(a.y); f[4] = bflo(a.z); f[5] = bfhi(a.z); f[6] = bflo(a.w); f[7] = bfhi(a.w);
;             f[8] = bflo(b.x); f[9] = bfhi(b.x); f[10] = bflo(b.y); f[11] = bfhi(b.y); f[12] = bflo(b.z); f[13] = bfhi(b.z); f[14] = bflo(b.w); f[15] = bfhi(b.w);
;             float s = 0.f;
; #pragma unroll
;             for (int i = 0; i < 16; ++i) s += f[i];
	v_lshlrev_b32_e32 v10, 16, v170
	v_add_f32_e32 v234, 0, v10
	v_and_b32_e32 v11, 0xffff0000, v170
	v_add_f32_e32 v234, v234, v11
	v_lshlrev_b32_e32 v10, 16, v171
	v_add_f32_e32 v234, v234, v10
	v_and_b32_e32 v11, 0xffff0000, v171
	v_add_f32_e32 v234, v234, v11
	v_lshlrev_b32_e32 v10, 16, v172
	v_add_f32_e32 v234, v234, v10
	v_and_b32_e32 v11, 0xffff0000, v172
	v_add_f32_e32 v234, v234, v11
	v_lshlrev_b32_e32 v10, 16, v173
	v_add_f32_e32 v234, v234, v10
	v_and_b32_e32 v11, 0xffff0000, v173
	v_add_f32_e32 v234, v234, v11
	v_lshlrev_b32_e32 v10, 16, v174
	v_add_f32_e32 v234, v234, v10
	v_and_b32_e32 v11, 0xffff0000, v174
	v_add_f32_e32 v234, v234, v11
	v_lshlrev_b32_e32 v10, 16, v175
	v_add_f32_e32 v234, v234, v10
	v_and_b32_e32 v11, 0xffff0000, v175
	v_add_f32_e32 v234, v234, v11
	v_lshlrev_b32_e32 v10, 16, v176
	v_add_f32_e32 v234, v234, v10
	v_and_b32_e32 v11, 0xffff0000, v176
	v_add_f32_e32 v234, v234, v11
	v_lshlrev_b32_e32 v10, 16, v177
	v_add_f32_e32 v234, v234, v10
	v_and_b32_e32 v11, 0xffff0000, v177
	v_add_f32_e32 v234, v234, v11
	s_waitcnt vmcnt(12)
	v_lshlrev_b32_e32 v10, 16, v178
	v_add_f32_e32 v235, 0, v10
	v_and_b32_e32 v11, 0xffff0000, v178
	v_add_f32_e32 v235, v235, v11
	v_lshlrev_b32_e32 v10, 16, v179
	v_add_f32_e32 v235, v235, v10
	v_and_b32_e32 v11, 0xffff0000, v179
	v_add_f32_e32 v235, v235, v11
	v_lshlrev_b32_e32 v10, 16, v180
	v_add_f32_e32 v235, v235, v10
	v_and_b32_e32 v11, 0xffff0000, v180
	v_add_f32_e32 v235, v235, v11
	v_lshlrev_b32_e32 v10, 16, v181
	v_add_f32_e32 v235, v235, v10
	v_and_b32_e32 v11, 0xffff0000, v181
	v_add_f32_e32 v235, v235, v11
	v_lshlrev_b32_e32 v10, 16, v182
	v_add_f32_e32 v235, v235, v10
	v_and_b32_e32 v11, 0xffff0000, v182
	v_add_f32_e32 v235, v235, v11
	v_lshlrev_b32_e32 v10, 16, v183
	v_add_f32_e32 v235, v235, v10
	v_and_b32_e32 v11, 0xffff0000, v183
	v_add_f32_e32 v235, v235, v11
	v_lshlrev_b32_e32 v10, 16, v184
	v_add_f32_e32 v235, v235, v10
	v_and_b32_e32 v11, 0xffff0000, v184
	v_add_f32_e32 v235, v235, v11
	v_lshlrev_b32_e32 v10, 16, v185
	v_add_f32_e32 v235, v235, v10
	v_and_b32_e32 v11, 0xffff0000, v185
	v_add_f32_e32 v235, v235, v11
	s_waitcnt vmcnt(10)
	v_lshlrev_b32_e32 v10, 16, v186
	v_add_f32_e32 v236, 0, v10
	v_and_b32_e32 v11, 0xffff0000, v186
	v_add_f32_e32 v236, v236, v11
	v_lshlrev_b32_e32 v10, 16, v187
	v_add_f32_e32 v236, v236, v10
	v_and_b32_e32 v11, 0xffff0000, v187
	v_add_f32_e32 v236, v236, v11
	v_lshlrev_b32_e32 v10, 16, v188
	v_add_f32_e32 v236, v236, v10
	v_and_b32_e32 v11, 0xffff0000, v188
	v_add_f32_e32 v236, v236, v11
	v_lshlrev_b32_e32 v10, 16, v189
	v_add_f32_e32 v236, v236, v10
	v_and_b32_e32 v11, 0xffff0000, v189
	v_add_f32_e32 v236, v236, v11
	v_lshlrev_b32_e32 v10, 16, v190
	v_add_f32_e32 v236, v236, v10
	v_and_b32_e32 v11, 0xffff0000, v190
	v_add_f32_e32 v236, v236, v11
	v_lshlrev_b32_e32 v10, 16, v191
	v_add_f32_e32 v236, v236, v10
	v_and_b32_e32 v11, 0xffff0000, v191
	v_add_f32_e32 v236, v236, v11
	v_lshlrev_b32_e32 v10, 16, v192
	v_add_f32_e32 v236, v236, v10
	v_and_b32_e32 v11, 0xffff0000, v192
	v_add_f32_e32 v236, v236, v11
	v_lshlrev_b32_e32 v10, 16, v193
	v_add_f32_e32 v236, v236, v10
	v_and_b32_e32 v11, 0xffff0000, v193
	v_add_f32_e32 v236, v236, v11
	s_waitcnt vmcnt(8)
	v_lshlrev_b32_e32 v10, 16, v194
	v_add_f32_e32 v237, 0, v10
	v_and_b32_e32 v11, 0xffff0000, v194
	v_add_f32_e32 v237, v237, v11
	v_lshlrev_b32_e32 v10, 16, v195
	v_add_f32_e32 v237, v237, v10
	v_and_b32_e32 v11, 0xffff0000, v195
	v_add_f32_e32 v237, v237, v11
	v_lshlrev_b32_e32 v10, 16, v196
	v_add_f32_e32 v237, v237, v10
	v_and_b32_e32 v11, 0xffff0000, v196
	v_add_f32_e32 v237, v237, v11
	v_lshlrev_b32_e32 v10, 16, v197
	v_add_f32_e32 v237, v237, v10
	v_and_b32_e32 v11, 0xffff0000, v197
	v_add_f32_e32 v237, v237, v11
	v_lshlrev_b32_e32 v10, 16, v198
	v_add_f32_e32 v237, v237, v10
	v_and_b32_e32 v11, 0xffff0000, v198
	v_add_f32_e32 v237, v237, v11
	v_lshlrev_b32_e32 v10, 16, v199
	v_add_f32_e32 v237, v237, v10
	v_and_b32_e32 v11, 0xffff0000, v199
	v_add_f32_e32 v237, v237, v11
	v_lshlrev_b32_e32 v10, 16, v200
	v_add_f32_e32 v237, v237, v10
	v_and_b32_e32 v11, 0xffff0000, v200
	v_add_f32_e32 v237, v237, v11
	v_lshlrev_b32_e32 v10, 16, v201
	v_add_f32_e32 v237, v237, v10
	v_and_b32_e32 v11, 0xffff0000, v201
	v_add_f32_e32 v237, v237, v11
	s_waitcnt vmcnt(6)
	v_lshlrev_b32_e32 v10, 16, v202
	v_add_f32_e32 v238, 0, v10
	v_and_b32_e32 v11, 0xffff0000, v202
	v_add_f32_e32 v238, v238, v11
	v_lshlrev_b32_e32 v10, 16, v203
	v_add_f32_e32 v238, v238, v10
	v_and_b32_e32 v11, 0xffff0000, v203
	v_add_f32_e32 v238, v238, v11
	v_lshlrev_b32_e32 v10, 16, v204
	v_add_f32_e32 v238, v238, v10
	v_and_b32_e32 v11, 0xffff0000, v204
	v_add_f32_e32 v238, v238, v11
	v_lshlrev_b32_e32 v10, 16, v205
	v_add_f32_e32 v238, v238, v10
	v_and_b32_e32 v11, 0xffff0000, v205
	v_add_f32_e32 v238, v238, v11
	v_lshlrev_b32_e32 v10, 16, v206
	v_add_f32_e32 v238, v238, v10
	v_and_b32_e32 v11, 0xffff0000, v206
	v_add_f32_e32 v238, v238, v11
	v_lshlrev_b32_e32 v10, 16, v207
	v_add_f32_e32 v238, v238, v10
	v_and_b32_e32 v11, 0xffff0000, v207
	v_add_f32_e32 v238, v238, v11
	v_lshlrev_b32_e32 v10, 16, v208
	v_add_f32_e32 v238, v238, v10
	v_and_b32_e32 v11, 0xffff0000, v208
	v_add_f32_e32 v238, v238, v11
	v_lshlrev_b32_e32 v10, 16, v209
	v_add_f32_e32 v238, v238, v10
	v_and_b32_e32 v11, 0xffff0000, v209
	v_add_f32_e32 v238, v238, v11
	s_waitcnt vmcnt(4)
; __device__ __forceinline__ float wave_sum(float v, int lane) { for (int o = 32; o >= 1; o >>= 1) v += shx(v, o, lane); return v; }
; __device__ __forceinline__ void sg_mfma_phase(int wave_s, const bf16_t* Z, bf16_t* SGO, const float* sgw, const float* sgb, const float* lng, const float* lnb, LAS unsigned char* lds) {
;     ...
;             for (int i = 0; i < 16; ++i) s += f[i];
;             const float mu = wave_sum(s, lane) * (1.0f / 1024.0f); float q = 0.f;
	v_lshlrev_b32_e32 v10, 16, v210
	v_add_f32_e32 v239, 0, v10
	v_and_b32_e32 v11, 0xffff0000, v210
	v_add_f32_e32 v239, v239, v11
	v_lshlrev_b32_e32 v10, 16, v211
	v_add_f32_e32 v239, v239, v10
	v_and_b32_e32 v11, 0xffff0000, v211
	v_add_f32_e32 v239, v239, v11
	v_lshlrev_b32_e32 v10, 16, v212
	v_add_f32_e32 v239, v239, v10
	v_and_b32_e32 v11, 0xffff0000, v212
	v_add_f32_e32 v239, v239, v11
	v_lshlrev_b32_e32 v10, 16, v213
	v_add_f32_e32 v239, v239, v10
	v_and_b32_e32 v11, 0xffff0000, v213
	v_add_f32_e32 v239, v239, v11
	v_lshlrev_b32_e32 v10, 16, v214
	v_add_f32_e32 v239, v239, v10
	v_and_b32_e32 v11, 0xffff0000, v214
	v_add_f32_e32 v239, v239, v11
	v_lshlrev_b32_e32 v10, 16, v215
	v_add_f32_e32 v239, v239, v10
	v_and_b32_e32 v11, 0xffff0000, v215
	v_add_f32_e32 v239, v239, v11
	v_lshlrev_b32_e32 v10, 16, v216
	v_add_f32_e32 v239, v239, v10
	v_and_b32_e32 v11, 0xffff0000, v216
	v_add_f32_e32 v239, v239, v11
	v_lshlrev_b32_e32 v10, 16, v217
	v_add_f32_e32 v239, v239, v10
	v_and_b32_e32 v11, 0xffff0000, v217
	v_add_f32_e32 v239, v239, v11
	s_waitcnt vmcnt(2)
	v_lshlrev_b32_e32 v10, 16, v218
	v_add_f32_e32 v240, 0, v10
	v_and_b32_e32 v11, 0xffff0000, v218
	v_add_f32_e32 v240, v240, v11
	v_lshlrev_b32_e32 v10, 16, v219
	v_add_f32_e32 v240, v240, v10
	v_and_b32_e32 v11, 0xffff0000, v219
	v_add_f32_e32 v240, v240, v11
	v_lshlrev_b32_e32 v10, 16, v220
	v_add_f32_e32 v240, v240, v10
	v_and_b32_e32 v11, 0xffff0000, v220
	v_add_f32_e32 v240, v240, v11
	v_lshlrev_b32_e32 v10, 16, v221
	v_add_f32_e32 v240, v240, v10
	v_and_b32_e32 v11, 0xffff0000, v221
	v_add_f32_e32 v240, v240, v11
	v_lshlrev_b32_e32 v10, 16, v222
	v_add_f32_e32 v240, v240, v10
	v_and_b32_e32 v11, 0xffff0000, v222
	v_add_f32_e32 v240, v240, v11
	v_lshlrev_b32_e32 v10, 16, v223
	v_add_f32_e32 v240, v240, v10
	v_and_b32_e32 v11, 0xffff0000, v223
	v_add_f32_e32 v240, v240, v11
	v_lshlrev_b32_e32 v10, 16, v224
	v_add_f32_e32 v240, v240, v10
	v_and_b32_e32 v11, 0xffff0000, v224
	v_add_f32_e32 v240, v240, v11
	v_lshlrev_b32_e32 v10, 16, v225
	v_add_f32_e32 v240, v240, v10
	v_and_b32_e32 v11, 0xffff0000, v225
	v_add_f32_e32 v240, v240, v11
	s_waitcnt vmcnt(0)
	v_lshlrev_b32_e32 v10, 16, v226
	v_add_f32_e32 v241, 0, v10
	v_and_b32_e32 v11, 0xffff0000, v226
	v_add_f32_e32 v241, v241, v11
	v_lshlrev_b32_e32 v10, 16, v227
	v_add_f32_e32 v241, v241, v10
	v_and_b32_e32 v11, 0xffff0000, v227
	v_add_f32_e32 v241, v241, v11
	v_lshlrev_b32_e32 v10, 16, v228
	v_add_f32_e32 v241, v241, v10
	v_and_b32_e32 v11, 0xffff0000, v228
	v_add_f32_e32 v241, v241, v11
	v_lshlrev_b32_e32 v10, 16, v229
	v_add_f32_e32 v241, v241, v10
	v_and_b32_e32 v11, 0xffff0000, v229
	v_add_f32_e32 v241, v241, v11
	v_lshlrev_b32_e32 v10, 16, v230
	v_add_f32_e32 v241, v241, v10
	v_and_b32_e32 v11, 0xffff0000, v230
	v_add_f32_e32 v241, v241, v11
	v_lshlrev_b32_e32 v10, 16, v231
	v_add_f32_e32 v241, v241, v10
	v_and_b32_e32 v11, 0xffff0000, v231
	v_add_f32_e32 v241, v241, v11
	v_lshlrev_b32_e32 v10, 16, v232
	v_add_f32_e32 v241, v241, v10
	v_and_b32_e32 v11, 0xffff0000, v232
	v_add_f32_e32 v241, v241, v11
	v_lshlrev_b32_e32 v10, 16, v233
	v_add_f32_e32 v241, v241, v10
	v_and_b32_e32 v11, 0xffff0000, v233
	v_add_f32_e32 v241, v241, v11
	ds_bpermute_b32 v2, v71, v234
	ds_bpermute_b32 v3, v71, v235
	ds_bpermute_b32 v4, v71, v236
	ds_bpermute_b32 v5, v71, v237
	ds_bpermute_b32 v6, v71, v238
	ds_bpermute_b32 v7, v71, v239
	ds_bpermute_b32 v8, v71, v240
	ds_bpermute_b32 v9, v71, v241
	s_waitcnt lgkmcnt(0)
	v_add_f32_e32 v234, v234, v2
	v_add_f32_e32 v235, v235, v3
	v_add_f32_e32 v236, v236, v4
	v_add_f32_e32 v237, v237, v5
	v_add_f32_e32 v238, v238, v6
	v_add_f32_e32 v239, v239, v7
	v_add_f32_e32 v240, v240, v8
	v_add_f32_e32 v241, v241, v9
	ds_bpermute_b32 v2, v72, v234
	ds_bpermute_b32 v3, v72, v235
	ds_bpermute_b32 v4, v72, v236
	ds_bpermute_b32 v5, v72, v237
	ds_bpermute_b32 v6, v72, v238
	ds_bpermute_b32 v7, v72, v239
	ds_bpermute_b32 v8, v72, v240
	ds_bpermute_b32 v9, v72, v241
	s_waitcnt lgkmcnt(0)
	v_add_f32_e32 v234, v234, v2
	v_add_f32_e32 v235, v235, v3
	v_add_f32_e32 v236, v236, v4
	v_add_f32_e32 v237, v237, v5
	v_add_f32_e32 v238, v238, v6
	v_add_f32_e32 v239, v239, v7
	v_add_f32_e32 v240, v240, v8
	v_add_f32_e32 v241, v241, v9
	ds_bpermute_b32 v2, v73, v234
	ds_bpermute_b32 v3, v73, v235
	ds_bpermute_b32 v4, v73, v236
	ds_bpermute_b32 v5, v73, v237
	ds_bpermute_b32 v6, v73, v238
	ds_bpermute_b32 v7, v73, v239
	ds_bpermute_b32 v8, v73, v240
	ds_bpermute_b32 v9, v73, v241
	s_waitcnt lgkmcnt(0)
	v_add_f32_e32 v234, v234, v2
	v_add_f32_e32 v235, v235, v3
	v_add_f32_e32 v236, v236, v4
	v_add_f32_e32 v237, v237, v5
	v_add_f32_e32 v238, v238, v6
	v_add_f32_e32 v239, v239, v7
	v_add_f32_e32 v240, v240, v8
	v_add_f32_e32 v241, v241, v9
	ds_bpermute_b32 v2, v74, v234
	ds_bpermute_b32 v3, v74, v235
	ds_bpermute_b32 v4, v74, v236
	ds_bpermute_b32 v5, v74, v237
	ds_bpermute_b32 v6, v74, v238
	ds_bpermute_b32 v7, v74, v239
	ds_bpermute_b32 v8, v74, v240
	ds_bpermute_b32 v9, v74, v241
	s_waitcnt lgkmcnt(0)
	v_add_f32_e32 v234, v234, v2
	v_add_f32_e32 v235, v235, v3
	v_add_f32_e32 v236, v236, v4
	v_add_f32_e32 v237, v237, v5
	v_add_f32_e32 v238, v238, v6
	v_add_f32_e32 v239, v239, v7
	v_add_f32_e32 v240, v240, v8
	v_add_f32_e32 v241, v241, v9
	ds_bpermute_b32 v2, v75, v234
	ds_bpermute_b32 v3, v75, v235
	ds_bpermute_b32 v4, v75, v236
	ds_bpermute_b32 v5, v75, v237
	ds_bpermute_b32 v6, v75, v238
	ds_bpermute_b32 v7, v75, v239
	ds_bpermute_b32 v8, v75, v240
	ds_bpermute_b32 v9, v75, v241
	s_waitcnt lgkmcnt(0)
; __device__ __forceinline__ float wave_sum(float v, int lane) { for (int o = 32; o >= 1; o >>= 1) v += shx(v, o, lane); return v; }
; __device__ __forceinline__ void sg_mfma_phase(int wave_s, const bf16_t* Z, bf16_t* SGO, const float* sgw, const float* sgb, const float* lng, const float* lnb, LAS unsigned char* lds) {
;     ...
;             const float mu = wave_sum(s, lane) * (1.0f / 1024.0f); float q = 0.f;
; #pragma unroll
;             for (int i = 0; i < 16; ++i) { const float dd = f[i] - mu; q += dd * dd; }
	v_add_f32_e32 v234, v234, v2
	v_add_f32_e32 v235, v235, v3
	v_add_f32_e32 v236, v236, v4
	v_add_f32_e32 v237, v237, v5
	v_add_f32_e32 v238, v238, v6
	v_add_f32_e32 v239, v239, v7
	v_add_f32_e32 v240, v240, v8
	v_add_f32_e32 v241, v241, v9
	ds_bpermute_b32 v2, v76, v234
	ds_bpermute_b32 v3, v76, v235
	ds_bpermute_b32 v4, v76, v236
	ds_bpermute_b32 v5, v76, v237
	ds_bpermute_b32 v6, v76, v238
	ds_bpermute_b32 v7, v76, v239
	ds_bpermute_b32 v8, v76, v240
	ds_bpermute_b32 v9, v76, v241
	s_waitcnt lgkmcnt(0)
	v_add_f32_e32 v234, v234, v2
	v_add_f32_e32 v235, v235, v3
	v_add_f32_e32 v236, v236, v4
	v_add_f32_e32 v237, v237, v5
	v_add_f32_e32 v238, v238, v6
	v_add_f32_e32 v239, v239, v7
	v_add_f32_e32 v240, v240, v8
	v_add_f32_e32 v241, v241, v9
	v_and_b32_e32 v10, 0xffff0000, v170
	v_fmac_f32_e32 v10, 0xba800000, v234
	v_mul_f32_e32 v242, v10, v10
	v_lshlrev_b32_e32 v10, 16, v170
	v_fmac_f32_e32 v10, 0xba800000, v234
	v_fmac_f32_e32 v242, v10, v10
	v_lshlrev_b32_e32 v10, 16, v171
	v_fmac_f32_e32 v10, 0xba800000, v234
	v_fmac_f32_e32 v242, v10, v10
	v_and_b32_e32 v10, 0xffff0000, v171
	v_fmac_f32_e32 v10, 0xba800000, v234
	v_fmac_f32_e32 v242, v10, v10
	v_lshlrev_b32_e32 v10, 16, v172
	v_fmac_f32_e32 v10, 0xba800000, v234
	v_fmac_f32_e32 v242, v10, v10
	v_and_b32_e32 v10, 0xffff0000, v172
	v_fmac_f32_e32 v10, 0xba800000, v234
	v_fmac_f32_e32 v242, v10, v10
	v_lshlrev_b32_e32 v10, 16, v173
	v_fmac_f32_e32 v10, 0xba800000, v234
	v_fmac_f32_e32 v242, v10, v10
	v_and_b32_e32 v10, 0xffff0000, v173
	v_fmac_f32_e32 v10, 0xba800000, v234
	v_fmac_f32_e32 v242, v10, v10
	v_lshlrev_b32_e32 v10, 16, v174
	v_fmac_f32_e32 v10, 0xba800000, v234
	v_fmac_f32_e32 v242, v10, v10
	v_and_b32_e32 v10, 0xffff0000, v174
	v_fmac_f32_e32 v10, 0xba800000, v234
	v_fmac_f32_e32 v242, v10, v10
	v_lshlrev_b32_e32 v10, 16, v175
	v_fmac_f32_e32 v10, 0xba800000, v234
	v_fmac_f32_e32 v242, v10, v10
	v_and_b32_e32 v10, 0xffff0000, v175
	v_fmac_f32_e32 v10, 0xba800000, v234
	v_fmac_f32_e32 v242, v10, v10
	v_lshlrev_b32_e32 v10, 16, v176
	v_fmac_f32_e32 v10, 0xba800000, v234
	v_fmac_f32_e32 v242, v10, v10
	v_and_b32_e32 v10, 0xffff0000, v176
	v_fmac_f32_e32 v10, 0xba800000, v234
	v_fmac_f32_e32 v242, v10, v10
	v_lshlrev_b32_e32 v10, 16, v177
	v_fmac_f32_e32 v10, 0xba800000, v234
	v_fmac_f32_e32 v242, v10, v10
	v_and_b32_e32 v10, 0xffff0000, v177
	v_fmac_f32_e32 v10, 0xba800000, v234
	v_fmac_f32_e32 v242, v10, v10
	v_and_b32_e32 v10, 0xffff0000, v178
	v_fmac_f32_e32 v10, 0xba800000, v235
	v_mul_f32_e32 v243, v10, v10
	v_lshlrev_b32_e32 v10, 16, v178
	v_fmac_f32_e32 v10, 0xba800000, v235
	v_fmac_f32_e32 v243, v10, v10
	v_lshlrev_b32_e32 v10, 16, v179
	v_fmac_f32_e32 v10, 0xba800000, v235
	v_fmac_f32_e32 v243, v10, v10
	v_and_b32_e32 v10, 0xffff0000, v179
	v_fmac_f32_e32 v10, 0xba800000, v235
	v_fmac_f32_e32 v243, v10, v10
	v_lshlrev_b32_e32 v10, 16, v180
	v_fmac_f32_e32 v10, 0xba800000, v235
	v_fmac_f32_e32 v243, v10, v10
	v_and_b32_e32 v10, 0xffff0000, v180
	v_fmac_f32_e32 v10, 0xba800000, v235
	v_fmac_f32_e32 v243, v10, v10
	v_lshlrev_b32_e32 v10, 16, v181
	v_fmac_f32_e32 v10, 0xba800000, v235
	v_fmac_f32_e32 v243, v10, v10
	v_and_b32_e32 v10, 0xffff0000, v181
	v_fmac_f32_e32 v10, 0xba800000, v235
	v_fmac_f32_e32 v243, v10, v10
	v_lshlrev_b32_e32 v10, 16, v182
	v_fmac_f32_e32 v10, 0xba800000, v235
	v_fmac_f32_e32 v243, v10, v10
	v_and_b32_e32 v10, 0xffff0000, v182
	v_fmac_f32_e32 v10, 0xba800000, v235
	v_fmac_f32_e32 v243, v10, v10
	v_lshlrev_b32_e32 v10, 16, v183
	v_fmac_f32_e32 v10, 0xba800000, v235
	v_fmac_f32_e32 v243, v10, v10
	v_and_b32_e32 v10, 0xffff0000, v183
	v_fmac_f32_e32 v10, 0xba800000, v235
	v_fmac_f32_e32 v243, v10, v10
	v_lshlrev_b32_e32 v10, 16, v184
	v_fmac_f32_e32 v10, 0xba800000, v235
	v_fmac_f32_e32 v243, v10, v10
	v_and_b32_e32 v10, 0xffff0000, v184
	v_fmac_f32_e32 v10, 0xba800000, v235
	v_fmac_f32_e32 v243, v10, v10
	v_lshlrev_b32_e32 v10, 16, v185
	v_fmac_f32_e32 v10, 0xba800000, v235
	v_fmac_f32_e32 v243, v10, v10
	v_and_b32_e32 v10, 0xffff0000, v185
	v_fmac_f32_e32 v10, 0xba800000, v235
	v_fmac_f32_e32 v243, v10, v10
	v_and_b32_e32 v10, 0xffff0000, v186
	v_fmac_f32_e32 v10, 0xba800000, v236
	v_mul_f32_e32 v244, v10, v10
	v_lshlrev_b32_e32 v10, 16, v186
	v_fmac_f32_e32 v10, 0xba800000, v236
	v_fmac_f32_e32 v244, v10, v10
	v_lshlrev_b32_e32 v10, 16, v187
	v_fmac_f32_e32 v10, 0xba800000, v236
	v_fmac_f32_e32 v244, v10, v10
	v_and_b32_e32 v10, 0xffff0000, v187
	v_fmac_f32_e32 v10, 0xba800000, v236
	v_fmac_f32_e32 v244, v10, v10
	v_lshlrev_b32_e32 v10, 16, v188
	v_fmac_f32_e32 v10, 0xba800000, v236
	v_fmac_f32_e32 v244, v10, v10
	v_and_b32_e32 v10, 0xffff0000, v188
	v_fmac_f32_e32 v10, 0xba800000, v236
	v_fmac_f32_e32 v244, v10, v10
	v_lshlrev_b32_e32 v10, 16, v189
	v_fmac_f32_e32 v10, 0xba800000, v236
	v_fmac_f32_e32 v244, v10, v10
	v_and_b32_e32 v10, 0xffff0000, v189
	v_fmac_f32_e32 v10, 0xba800000, v236
	v_fmac_f32_e32 v244, v10, v10
	v_lshlrev_b32_e32 v10, 16, v190
	v_fmac_f32_e32 v10, 0xba800000, v236
	v_fmac_f32_e32 v244, v10, v10
	v_and_b32_e32 v10, 0xffff0000, v190
	v_fmac_f32_e32 v10, 0xba800000, v236
	v_fmac_f32_e32 v244, v10, v10
	v_lshlrev_b32_e32 v10, 16, v191
	v_fmac_f32_e32 v10, 0xba800000, v236
	v_fmac_f32_e32 v244, v10, v10
	v_and_b32_e32 v10, 0xffff0000, v191
	v_fmac_f32_e32 v10, 0xba800000, v236
	v_fmac_f32_e32 v244, v10, v10
	v_lshlrev_b32_e32 v10, 16, v192
	v_fmac_f32_e32 v10, 0xba800000, v236
	v_fmac_f32_e32 v244, v10, v10
	v_and_b32_e32 v10, 0xffff0000, v192
	v_fmac_f32_e32 v10, 0xba800000, v236
	v_fmac_f32_e32 v244, v10, v10
	v_lshlrev_b32_e32 v10, 16, v193
	v_fmac_f32_e32 v10, 0xba800000, v236
	v_fmac_f32_e32 v244, v10, v10
; __device__ __forceinline__ float wave_sum(float v, int lane) { for (int o = 32; o >= 1; o >>= 1) v += shx(v, o, lane); return v; }
; __device__ __forceinline__ void sg_mfma_phase(int wave_s, const bf16_t* Z, bf16_t* SGO, const float* sgw, const float* sgb, const float* lng, const float* lnb, LAS unsigned char* lds) {
;     ...
;             const float mu = wave_sum(s, lane) * (1.0f / 1024.0f); float q = 0.f;
; #pragma unroll
;             for (int i = 0; i < 16; ++i) { const float dd = f[i] - mu; q += dd * dd; }
;             q = wave_sum(q, lane);
	v_and_b32_e32 v10, 0xffff0000, v193
	v_fmac_f32_e32 v10, 0xba800000, v236
	v_fmac_f32_e32 v244, v10, v10
	v_and_b32_e32 v10, 0xffff0000, v194
	v_fmac_f32_e32 v10, 0xba800000, v237
	v_mul_f32_e32 v245, v10, v10
	v_lshlrev_b32_e32 v10, 16, v194
	v_fmac_f32_e32 v10, 0xba800000, v237
	v_fmac_f32_e32 v245, v10, v10
	v_lshlrev_b32_e32 v10, 16, v195
	v_fmac_f32_e32 v10, 0xba800000, v237
	v_fmac_f32_e32 v245, v10, v10
	v_and_b32_e32 v10, 0xffff0000, v195
	v_fmac_f32_e32 v10, 0xba800000, v237
	v_fmac_f32_e32 v245, v10, v10
	v_lshlrev_b32_e32 v10, 16, v196
	v_fmac_f32_e32 v10, 0xba800000, v237
	v_fmac_f32_e32 v245, v10, v10
	v_and_b32_e32 v10, 0xffff0000, v196
	v_fmac_f32_e32 v10, 0xba800000, v237
	v_fmac_f32_e32 v245, v10, v10
	v_lshlrev_b32_e32 v10, 16, v197
	v_fmac_f32_e32 v10, 0xba800000, v237
	v_fmac_f32_e32 v245, v10, v10
	v_and_b32_e32 v10, 0xffff0000, v197
	v_fmac_f32_e32 v10, 0xba800000, v237
	v_fmac_f32_e32 v245, v10, v10
	v_lshlrev_b32_e32 v10, 16, v198
	v_fmac_f32_e32 v10, 0xba800000, v237
	v_fmac_f32_e32 v245, v10, v10
	v_and_b32_e32 v10, 0xffff0000, v198
	v_fmac_f32_e32 v10, 0xba800000, v237
	v_fmac_f32_e32 v245, v10, v10
	v_lshlrev_b32_e32 v10, 16, v199
	v_fmac_f32_e32 v10, 0xba800000, v237
	v_fmac_f32_e32 v245, v10, v10
	v_and_b32_e32 v10, 0xffff0000, v199
	v_fmac_f32_e32 v10, 0xba800000, v237
	v_fmac_f32_e32 v245, v10, v10
	v_lshlrev_b32_e32 v10, 16, v200
	v_fmac_f32_e32 v10, 0xba800000, v237
	v_fmac_f32_e32 v245, v10, v10
	v_and_b32_e32 v10, 0xffff0000, v200
	v_fmac_f32_e32 v10, 0xba800000, v237
	v_fmac_f32_e32 v245, v10, v10
	v_lshlrev_b32_e32 v10, 16, v201
	v_fmac_f32_e32 v10, 0xba800000, v237
	v_fmac_f32_e32 v245, v10, v10
	v_and_b32_e32 v10, 0xffff0000, v201
	v_fmac_f32_e32 v10, 0xba800000, v237
	v_fmac_f32_e32 v245, v10, v10
	v_and_b32_e32 v10, 0xffff0000, v202
	v_fmac_f32_e32 v10, 0xba800000, v238
	v_mul_f32_e32 v246, v10, v10
	v_lshlrev_b32_e32 v10, 16, v202
	v_fmac_f32_e32 v10, 0xba800000, v238
	v_fmac_f32_e32 v246, v10, v10
	v_lshlrev_b32_e32 v10, 16, v203
	v_fmac_f32_e32 v10, 0xba800000, v238
	v_fmac_f32_e32 v246, v10, v10
	v_and_b32_e32 v10, 0xffff0000, v203
	v_fmac_f32_e32 v10, 0xba800000, v238
	v_fmac_f32_e32 v246, v10, v10
	v_lshlrev_b32_e32 v10, 16, v204
	v_fmac_f32_e32 v10, 0xba800000, v238
	v_fmac_f32_e32 v246, v10, v10
	v_and_b32_e32 v10, 0xffff0000, v204
	v_fmac_f32_e32 v10, 0xba800000, v238
	v_fmac_f32_e32 v246, v10, v10
	v_lshlrev_b32_e32 v10, 16, v205
	v_fmac_f32_e32 v10, 0xba800000, v238
	v_fmac_f32_e32 v246, v10, v10
	v_and_b32_e32 v10, 0xffff0000, v205
	v_fmac_f32_e32 v10, 0xba800000, v238
	v_fmac_f32_e32 v246, v10, v10
	v_lshlrev_b32_e32 v10, 16, v206
	v_fmac_f32_e32 v10, 0xba800000, v238
	v_fmac_f32_e32 v246, v10, v10
	v_and_b32_e32 v10, 0xffff0000, v206
	v_fmac_f32_e32 v10, 0xba800000, v238
	v_fmac_f32_e32 v246, v10, v10
	v_lshlrev_b32_e32 v10, 16, v207
	v_fmac_f32_e32 v10, 0xba800000, v238
	v_fmac_f32_e32 v246, v10, v10
	v_and_b32_e32 v10, 0xffff0000, v207
	v_fmac_f32_e32 v10, 0xba800000, v238
	v_fmac_f32_e32 v246, v10, v10
	v_lshlrev_b32_e32 v10, 16, v208
	v_fmac_f32_e32 v10, 0xba800000, v238
	v_fmac_f32_e32 v246, v10, v10
	v_and_b32_e32 v10, 0xffff0000, v208
	v_fmac_f32_e32 v10, 0xba800000, v238
	v_fmac_f32_e32 v246, v10, v10
	v_lshlrev_b32_e32 v10, 16, v209
	v_fmac_f32_e32 v10, 0xba800000, v238
	v_fmac_f32_e32 v246, v10, v10
	v_and_b32_e32 v10, 0xffff0000, v209
	v_fmac_f32_e32 v10, 0xba800000, v238
	v_fmac_f32_e32 v246, v10, v10
	v_and_b32_e32 v10, 0xffff0000, v210
	v_fmac_f32_e32 v10, 0xba800000, v239
	v_mul_f32_e32 v247, v10, v10
	v_lshlrev_b32_e32 v10, 16, v210
	v_fmac_f32_e32 v10, 0xba800000, v239
	v_fmac_f32_e32 v247, v10, v10
	v_lshlrev_b32_e32 v10, 16, v211
	v_fmac_f32_e32 v10, 0xba800000, v239
	v_fmac_f32_e32 v247, v10, v10
	v_and_b32_e32 v10, 0xffff0000, v211
	v_fmac_f32_e32 v10, 0xba800000, v239
	v_fmac_f32_e32 v247, v10, v10
	v_lshlrev_b32_e32 v10, 16, v212
	v_fmac_f32_e32 v10, 0xba800000, v239
	v_fmac_f32_e32 v247, v10, v10
	v_and_b32_e32 v10, 0xffff0000, v212
	v_fmac_f32_e32 v10, 0xba800000, v239
	v_fmac_f32_e32 v247, v10, v10
	v_lshlrev_b32_e32 v10, 16, v213
	v_fmac_f32_e32 v10, 0xba800000, v239
	v_fmac_f32_e32 v247, v10, v10
	v_and_b32_e32 v10, 0xffff0000, v213
	v_fmac_f32_e32 v10, 0xba800000, v239
	v_fmac_f32_e32 v247, v10, v10
	v_lshlrev_b32_e32 v10, 16, v214
	v_fmac_f32_e32 v10, 0xba800000, v239
	v_fmac_f32_e32 v247, v10, v10
	v_and_b32_e32 v10, 0xffff0000, v214
	v_fmac_f32_e32 v10, 0xba800000, v239
	v_fmac_f32_e32 v247, v10, v10
	v_lshlrev_b32_e32 v10, 16, v215
	v_fmac_f32_e32 v10, 0xba800000, v239
	v_fmac_f32_e32 v247, v10, v10
	v_and_b32_e32 v10, 0xffff0000, v215
	v_fmac_f32_e32 v10, 0xba800000, v239
	v_fmac_f32_e32 v247, v10, v10
	v_lshlrev_b32_e32 v10, 16, v216
	v_fmac_f32_e32 v10, 0xba800000, v239
	v_fmac_f32_e32 v247, v10, v10
	v_and_b32_e32 v10, 0xffff0000, v216
	v_fmac_f32_e32 v10, 0xba800000, v239
	v_fmac_f32_e32 v247, v10, v10
	v_lshlrev_b32_e32 v10, 16, v217
	v_fmac_f32_e32 v10, 0xba800000, v239
	v_fmac_f32_e32 v247, v10, v10
	v_and_b32_e32 v10, 0xffff0000, v217
	v_fmac_f32_e32 v10, 0xba800000, v239
	v_fmac_f32_e32 v247, v10, v10
	v_and_b32_e32 v10, 0xffff0000, v218
	v_fmac_f32_e32 v10, 0xba800000, v240
	v_mul_f32_e32 v248, v10, v10
	v_lshlrev_b32_e32 v10, 16, v218
	v_fmac_f32_e32 v10, 0xba800000, v240
	v_fmac_f32_e32 v248, v10, v10
	v_lshlrev_b32_e32 v10, 16, v219
	v_fmac_f32_e32 v10, 0xba800000, v240
	v_fmac_f32_e32 v248, v10, v10
	v_and_b32_e32 v10, 0xffff0000, v219
	v_fmac_f32_e32 v10, 0xba800000, v240
	v_fmac_f32_e32 v248, v10, v10
	v_lshlrev_b32_e32 v10, 16, v220
	v_fmac_f32_e32 v10, 0xba800000, v240
	v_fmac_f32_e32 v248, v10, v10
	v_and_b32_e32 v10, 0xffff0000, v220
; __device__ __forceinline__ float wave_sum(float v, int lane) { for (int o = 32; o >= 1; o >>= 1) v += shx(v, o, lane); return v; }
; __device__ __forceinline__ void sg_mfma_phase(int wave_s, const bf16_t* Z, bf16_t* SGO, const float* sgw, const float* sgb, const float* lng, const float* lnb, LAS unsigned char* lds) {
;     ...
;             const float mu = wave_sum(s, lane) * (1.0f / 1024.0f); float q = 0.f;
; #pragma unroll
;             for (int i = 0; i < 16; ++i) { const float dd = f[i] - mu; q += dd * dd; }
;             q = wave_sum(q, lane);
	v_fmac_f32_e32 v10, 0xba800000, v240
	v_fmac_f32_e32 v248, v10, v10
	v_lshlrev_b32_e32 v10, 16, v221
	v_fmac_f32_e32 v10, 0xba800000, v240
	v_fmac_f32_e32 v248, v10, v10
	v_and_b32_e32 v10, 0xffff0000, v221
	v_fmac_f32_e32 v10, 0xba800000, v240
	v_fmac_f32_e32 v248, v10, v10
	v_lshlrev_b32_e32 v10, 16, v222
	v_fmac_f32_e32 v10, 0xba800000, v240
	v_fmac_f32_e32 v248, v10, v10
	v_and_b32_e32 v10, 0xffff0000, v222
	v_fmac_f32_e32 v10, 0xba800000, v240
	v_fmac_f32_e32 v248, v10, v10
	v_lshlrev_b32_e32 v10, 16, v223
	v_fmac_f32_e32 v10, 0xba800000, v240
	v_fmac_f32_e32 v248, v10, v10
	v_and_b32_e32 v10, 0xffff0000, v223
	v_fmac_f32_e32 v10, 0xba800000, v240
	v_fmac_f32_e32 v248, v10, v10
	v_lshlrev_b32_e32 v10, 16, v224
	v_fmac_f32_e32 v10, 0xba800000, v240
	v_fmac_f32_e32 v248, v10, v10
	v_and_b32_e32 v10, 0xffff0000, v224
	v_fmac_f32_e32 v10, 0xba800000, v240
	v_fmac_f32_e32 v248, v10, v10
	v_lshlrev_b32_e32 v10, 16, v225
	v_fmac_f32_e32 v10, 0xba800000, v240
	v_fmac_f32_e32 v248, v10, v10
	v_and_b32_e32 v10, 0xffff0000, v225
	v_fmac_f32_e32 v10, 0xba800000, v240
	v_fmac_f32_e32 v248, v10, v10
	v_and_b32_e32 v10, 0xffff0000, v226
	v_fmac_f32_e32 v10, 0xba800000, v241
	v_mul_f32_e32 v249, v10, v10
	v_lshlrev_b32_e32 v10, 16, v226
	v_fmac_f32_e32 v10, 0xba800000, v241
	v_fmac_f32_e32 v249, v10, v10
	v_lshlrev_b32_e32 v10, 16, v227
	v_fmac_f32_e32 v10, 0xba800000, v241
	v_fmac_f32_e32 v249, v10, v10
	v_and_b32_e32 v10, 0xffff0000, v227
	v_fmac_f32_e32 v10, 0xba800000, v241
	v_fmac_f32_e32 v249, v10, v10
	v_lshlrev_b32_e32 v10, 16, v228
	v_fmac_f32_e32 v10, 0xba800000, v241
	v_fmac_f32_e32 v249, v10, v10
	v_and_b32_e32 v10, 0xffff0000, v228
	v_fmac_f32_e32 v10, 0xba800000, v241
	v_fmac_f32_e32 v249, v10, v10
	v_lshlrev_b32_e32 v10, 16, v229
	v_fmac_f32_e32 v10, 0xba800000, v241
	v_fmac_f32_e32 v249, v10, v10
	v_and_b32_e32 v10, 0xffff0000, v229
	v_fmac_f32_e32 v10, 0xba800000, v241
	v_fmac_f32_e32 v249, v10, v10
	v_lshlrev_b32_e32 v10, 16, v230
	v_fmac_f32_e32 v10, 0xba800000, v241
	v_fmac_f32_e32 v249, v10, v10
	v_and_b32_e32 v10, 0xffff0000, v230
	v_fmac_f32_e32 v10, 0xba800000, v241
	v_fmac_f32_e32 v249, v10, v10
	v_lshlrev_b32_e32 v10, 16, v231
	v_fmac_f32_e32 v10, 0xba800000, v241
	v_fmac_f32_e32 v249, v10, v10
	v_and_b32_e32 v10, 0xffff0000, v231
	v_fmac_f32_e32 v10, 0xba800000, v241
	v_fmac_f32_e32 v249, v10, v10
	v_lshlrev_b32_e32 v10, 16, v232
	v_fmac_f32_e32 v10, 0xba800000, v241
	v_fmac_f32_e32 v249, v10, v10
	v_and_b32_e32 v10, 0xffff0000, v232
	v_fmac_f32_e32 v10, 0xba800000, v241
	v_fmac_f32_e32 v249, v10, v10
	v_lshlrev_b32_e32 v10, 16, v233
	v_fmac_f32_e32 v10, 0xba800000, v241
	v_fmac_f32_e32 v249, v10, v10
	v_and_b32_e32 v10, 0xffff0000, v233
	v_fmac_f32_e32 v10, 0xba800000, v241
	v_fmac_f32_e32 v249, v10, v10
	ds_bpermute_b32 v2, v71, v242
	ds_bpermute_b32 v3, v71, v243
	ds_bpermute_b32 v4, v71, v244
	ds_bpermute_b32 v5, v71, v245
	ds_bpermute_b32 v6, v71, v246
	ds_bpermute_b32 v7, v71, v247
	ds_bpermute_b32 v8, v71, v248
	ds_bpermute_b32 v9, v71, v249
	s_waitcnt lgkmcnt(0)
	v_add_f32_e32 v242, v242, v2
	v_add_f32_e32 v243, v243, v3
	v_add_f32_e32 v244, v244, v4
	v_add_f32_e32 v245, v245, v5
	v_add_f32_e32 v246, v246, v6
	v_add_f32_e32 v247, v247, v7
	v_add_f32_e32 v248, v248, v8
	v_add_f32_e32 v249, v249, v9
	ds_bpermute_b32 v2, v72, v242
	ds_bpermute_b32 v3, v72, v243
	ds_bpermute_b32 v4, v72, v244
	ds_bpermute_b32 v5, v72, v245
	ds_bpermute_b32 v6, v72, v246
	ds_bpermute_b32 v7, v72, v247
	ds_bpermute_b32 v8, v72, v248
	ds_bpermute_b32 v9, v72, v249
	s_waitcnt lgkmcnt(0)
	v_add_f32_e32 v242, v242, v2
	v_add_f32_e32 v243, v243, v3
	v_add_f32_e32 v244, v244, v4
	v_add_f32_e32 v245, v245, v5
	v_add_f32_e32 v246, v246, v6
	v_add_f32_e32 v247, v247, v7
	v_add_f32_e32 v248, v248, v8
	v_add_f32_e32 v249, v249, v9
	ds_bpermute_b32 v2, v73, v242
	ds_bpermute_b32 v3, v73, v243
	ds_bpermute_b32 v4, v73, v244
	ds_bpermute_b32 v5, v73, v245
	ds_bpermute_b32 v6, v73, v246
	ds_bpermute_b32 v7, v73, v247
	ds_bpermute_b32 v8, v73, v248
	ds_bpermute_b32 v9, v73, v249
	s_waitcnt lgkmcnt(0)
	v_add_f32_e32 v242, v242, v2
	v_add_f32_e32 v243, v243, v3
	v_add_f32_e32 v244, v244, v4
	v_add_f32_e32 v245, v245, v5
	v_add_f32_e32 v246, v246, v6
	v_add_f32_e32 v247, v247, v7
	v_add_f32_e32 v248, v248, v8
	v_add_f32_e32 v249, v249, v9
	ds_bpermute_b32 v2, v74, v242
	ds_bpermute_b32 v3, v74, v243
	ds_bpermute_b32 v4, v74, v244
	ds_bpermute_b32 v5, v74, v245
	ds_bpermute_b32 v6, v74, v246
	ds_bpermute_b32 v7, v74, v247
	ds_bpermute_b32 v8, v74, v248
	ds_bpermute_b32 v9, v74, v249
	s_waitcnt lgkmcnt(0)
	v_add_f32_e32 v242, v242, v2
	v_add_f32_e32 v243, v243, v3
	v_add_f32_e32 v244, v244, v4
	v_add_f32_e32 v245, v245, v5
	v_add_f32_e32 v246, v246, v6
	v_add_f32_e32 v247, v247, v7
	v_add_f32_e32 v248, v248, v8
	v_add_f32_e32 v249, v249, v9
	ds_bpermute_b32 v2, v75, v242
	ds_bpermute_b32 v3, v75, v243
	ds_bpermute_b32 v4, v75, v244
	ds_bpermute_b32 v5, v75, v245
	ds_bpermute_b32 v6, v75, v246
	ds_bpermute_b32 v7, v75, v247
	ds_bpermute_b32 v8, v75, v248
	ds_bpermute_b32 v9, v75, v249
	s_waitcnt lgkmcnt(0)
	v_add_f32_e32 v242, v242, v2
	v_add_f32_e32 v243, v243, v3
	v_add_f32_e32 v244, v244, v4
	v_add_f32_e32 v245, v245, v5
	v_add_f32_e32 v246, v246, v6
	v_add_f32_e32 v247, v247, v7
	v_add_f32_e32 v248, v248, v8
	v_add_f32_e32 v249, v249, v9
	ds_bpermute_b32 v2, v76, v242
	ds_bpermute_b32 v3, v76, v243
	ds_bpermute_b32 v4, v76, v244
	ds_bpermute_b32 v5, v76, v245
	ds_bpermute_b32 v6, v76, v246
	ds_bpermute_b32 v7, v76, v247
	ds_bpermute_b32 v8, v76, v248
	ds_bpermute_b32 v9, v76, v249
	s_waitcnt lgkmcnt(0)
; __device__ __forceinline__ float wave_sum(float v, int lane) { for (int o = 32; o >= 1; o >>= 1) v += shx(v, o, lane); return v; }
; __device__ __forceinline__ void sg_mfma_phase(int wave_s, const bf16_t* Z, bf16_t* SGO, const float* sgw, const float* sgb, const float* lng, const float* lnb, LAS unsigned char* lds) {
;     ...
;             q = wave_sum(q, lane);
;             if (lane == 0) { st[2 * j] = mu; st[2 * j + 1] = 1.0f / sqrtf(q * (1.0f / 1024.0f) + 1e-6f); } }
	v_add_f32_e32 v242, v242, v2
	v_add_f32_e32 v243, v243, v3
	v_add_f32_e32 v244, v244, v4
	v_add_f32_e32 v245, v245, v5
	v_add_f32_e32 v246, v246, v6
	v_add_f32_e32 v247, v247, v7
	v_add_f32_e32 v248, v248, v8
	v_add_f32_e32 v249, v249, v9
	s_and_saveexec_b64 s[16:17], s[6:7]
	v_mov_b32_e32 v2, v234
	v_mov_b32_e32 v3, v242
	v_fmamk_f32 v3, v3, 0x3a800000, v164
	v_mul_f32_e32 v4, 0x4f800000, v3
	v_cmp_gt_f32_e32 vcc, s18, v3
	v_mul_f32_e32 v2, 0x3a800000, v2
	s_nop 0
	v_cndmask_b32_e32 v3, v3, v4, vcc
	v_sqrt_f32_e32 v4, v3
	s_nop 0
	v_add_u32_e32 v5, -1, v4
	v_fma_f32 v7, -v5, v4, v3
	v_add_u32_e32 v6, 1, v4
	v_cmp_ge_f32_e64 s[10:11], 0, v7
	s_nop 1
	v_cndmask_b32_e64 v5, v4, v5, s[10:11]
	v_fma_f32 v4, -v6, v4, v3
	v_cmp_lt_f32_e64 s[10:11], 0, v4
	s_nop 1
	v_cndmask_b32_e64 v4, v5, v6, s[10:11]
	v_mul_f32_e32 v5, 0x37800000, v4
	v_cndmask_b32_e32 v4, v4, v5, vcc
	v_cmp_class_f32_e32 vcc, v3, v165
	v_add_u32_e32 v6, 0x40, v77
	s_nop 0
	v_cndmask_b32_e32 v3, v4, v3, vcc
	v_div_scale_f32 v4, s[10:11], v3, v3, 1.0
	v_rcp_f32_e32 v5, v4
	s_nop 0
	v_fma_f32 v7, -v4, v5, 1.0
	v_fmac_f32_e32 v5, v7, v5
	v_div_scale_f32 v7, vcc, 1.0, v3, 1.0
	v_mul_f32_e32 v8, v7, v5
	v_fma_f32 v9, -v4, v8, v7
	v_fmac_f32_e32 v8, v9, v5
	v_fma_f32 v4, -v4, v8, v7
	v_div_fmas_f32 v4, v4, v5, v8
	v_div_fixup_f32 v3, v4, v3, 1.0
	ds_write_b64 v6, v[2:3]
	v_mov_b32_e32 v2, v235
	v_mov_b32_e32 v3, v243
	v_fmamk_f32 v3, v3, 0x3a800000, v164
	v_mul_f32_e32 v4, 0x4f800000, v3
	v_cmp_gt_f32_e32 vcc, s18, v3
	v_mul_f32_e32 v2, 0x3a800000, v2
	s_nop 0
	v_cndmask_b32_e32 v3, v3, v4, vcc
	v_sqrt_f32_e32 v4, v3
	s_nop 0
	v_add_u32_e32 v5, -1, v4
	v_fma_f32 v7, -v5, v4, v3
	v_add_u32_e32 v6, 1, v4
	v_cmp_ge_f32_e64 s[10:11], 0, v7
	s_nop 1
	v_cndmask_b32_e64 v5, v4, v5, s[10:11]
	v_fma_f32 v4, -v6, v4, v3
	v_cmp_lt_f32_e64 s[10:11], 0, v4
	s_nop 1
	v_cndmask_b32_e64 v4, v5, v6, s[10:11]
	v_mul_f32_e32 v5, 0x37800000, v4
	v_cndmask_b32_e32 v4, v4, v5, vcc
	v_cmp_class_f32_e32 vcc, v3, v165
	v_add_u32_e32 v6, 0x48, v77
	s_nop 0
	v_cndmask_b32_e32 v3, v4, v3, vcc
	v_div_scale_f32 v4, s[10:11], v3, v3, 1.0
	v_rcp_f32_e32 v5, v4
	s_nop 0
	v_fma_f32 v7, -v4, v5, 1.0
	v_fmac_f32_e32 v5, v7, v5
	v_div_scale_f32 v7, vcc, 1.0, v3, 1.0
	v_mul_f32_e32 v8, v7, v5
	v_fma_f32 v9, -v4, v8, v7
	v_fmac_f32_e32 v8, v9, v5
	v_fma_f32 v4, -v4, v8, v7
	v_div_fmas_f32 v4, v4, v5, v8
	v_div_fixup_f32 v3, v4, v3, 1.0
	ds_write_b64 v6, v[2:3]
	v_mov_b32_e32 v2, v236
	v_mov_b32_e32 v3, v244
	v_fmamk_f32 v3, v3, 0x3a800000, v164
	v_mul_f32_e32 v4, 0x4f800000, v3
	v_cmp_gt_f32_e32 vcc, s18, v3
	v_mul_f32_e32 v2, 0x3a800000, v2
	s_nop 0
	v_cndmask_b32_e32 v3, v3, v4, vcc
	v_sqrt_f32_e32 v4, v3
	s_nop 0
	v_add_u32_e32 v5, -1, v4
	v_fma_f32 v7, -v5, v4, v3
	v_add_u32_e32 v6, 1, v4
	v_cmp_ge_f32_e64 s[10:11], 0, v7
	s_nop 1
	v_cndmask_b32_e64 v5, v4, v5, s[10:11]
	v_fma_f32 v4, -v6, v4, v3
	v_cmp_lt_f32_e64 s[10:11], 0, v4
	s_nop 1
	v_cndmask_b32_e64 v4, v5, v6, s[10:11]
	v_mul_f32_e32 v5, 0x37800000, v4
	v_cndmask_b32_e32 v4, v4, v5, vcc
	v_cmp_class_f32_e32 vcc, v3, v165
	v_add_u32_e32 v6, 0x50, v77
	s_nop 0
	v_cndmask_b32_e32 v3, v4, v3, vcc
	v_div_scale_f32 v4, s[10:11], v3, v3, 1.0
	v_rcp_f32_e32 v5, v4
	s_nop 0
	v_fma_f32 v7, -v4, v5, 1.0
	v_fmac_f32_e32 v5, v7, v5
	v_div_scale_f32 v7, vcc, 1.0, v3, 1.0
	v_mul_f32_e32 v8, v7, v5
	v_fma_f32 v9, -v4, v8, v7
	v_fmac_f32_e32 v8, v9, v5
	v_fma_f32 v4, -v4, v8, v7
	v_div_fmas_f32 v4, v4, v5, v8
	v_div_fixup_f32 v3, v4, v3, 1.0
	ds_write_b64 v6, v[2:3]
	v_mov_b32_e32 v2, v237
	v_mov_b32_e32 v3, v245
	v_fmamk_f32 v3, v3, 0x3a800000, v164
	v_mul_f32_e32 v4, 0x4f800000, v3
	v_cmp_gt_f32_e32 vcc, s18, v3
	v_mul_f32_e32 v2, 0x3a800000, v2
	s_nop 0
	v_cndmask_b32_e32 v3, v3, v4, vcc
	v_sqrt_f32_e32 v4, v3
	s_nop 0
	v_add_u32_e32 v5, -1, v4
	v_fma_f32 v7, -v5, v4, v3
	v_add_u32_e32 v6, 1, v4
	v_cmp_ge_f32_e64 s[10:11], 0, v7
	s_nop 1
	v_cndmask_b32_e64 v5, v4, v5, s[10:11]
	v_fma_f32 v4, -v6, v4, v3
	v_cmp_lt_f32_e64 s[10:11], 0, v4
	s_nop 1
	v_cndmask_b32_e64 v4, v5, v6, s[10:11]
	v_mul_f32_e32 v5, 0x37800000, v4
	v_cndmask_b32_e32 v4, v4, v5, vcc
	v_cmp_class_f32_e32 vcc, v3, v165
	v_add_u32_e32 v6, 0x58, v77
	s_nop 0
	v_cndmask_b32_e32 v3, v4, v3, vcc
	v_div_scale_f32 v4, s[10:11], v3, v3, 1.0
	v_rcp_f32_e32 v5, v4
	s_nop 0
	v_fma_f32 v7, -v4, v5, 1.0
	v_fmac_f32_e32 v5, v7, v5
	v_div_scale_f32 v7, vcc, 1.0, v3, 1.0
	v_mul_f32_e32 v8, v7, v5
	v_fma_f32 v9, -v4, v8, v7
	v_fmac_f32_e32 v8, v9, v5
; __device__ __forceinline__ float wave_sum(float v, int lane) { for (int o = 32; o >= 1; o >>= 1) v += shx(v, o, lane); return v; }
; __device__ __forceinline__ void sg_mfma_phase(int wave_s, const bf16_t* Z, bf16_t* SGO, const float* sgw, const float* sgb, const float* lng, const float* lnb, LAS unsigned char* lds) {
;     ...
;             q = wave_sum(q, lane);
;             if (lane == 0) { st[2 * j] = mu; st[2 * j + 1] = 1.0f / sqrtf(q * (1.0f / 1024.0f) + 1e-6f); } }
	v_fma_f32 v4, -v4, v8, v7
	v_div_fmas_f32 v4, v4, v5, v8
	v_div_fixup_f32 v3, v4, v3, 1.0
	ds_write_b64 v6, v[2:3]
	v_mov_b32_e32 v2, v238
	v_mov_b32_e32 v3, v246
	v_fmamk_f32 v3, v3, 0x3a800000, v164
	v_mul_f32_e32 v4, 0x4f800000, v3
	v_cmp_gt_f32_e32 vcc, s18, v3
	v_mul_f32_e32 v2, 0x3a800000, v2
	s_nop 0
	v_cndmask_b32_e32 v3, v3, v4, vcc
	v_sqrt_f32_e32 v4, v3
	s_nop 0
	v_add_u32_e32 v5, -1, v4
	v_fma_f32 v7, -v5, v4, v3
	v_add_u32_e32 v6, 1, v4
	v_cmp_ge_f32_e64 s[10:11], 0, v7
	s_nop 1
	v_cndmask_b32_e64 v5, v4, v5, s[10:11]
	v_fma_f32 v4, -v6, v4, v3
	v_cmp_lt_f32_e64 s[10:11], 0, v4
	s_nop 1
	v_cndmask_b32_e64 v4, v5, v6, s[10:11]
	v_mul_f32_e32 v5, 0x37800000, v4
	v_cndmask_b32_e32 v4, v4, v5, vcc
	v_cmp_class_f32_e32 vcc, v3, v165
	v_add_u32_e32 v6, 0x60, v77
	s_nop 0
	v_cndmask_b32_e32 v3, v4, v3, vcc
	v_div_scale_f32 v4, s[10:11], v3, v3, 1.0
	v_rcp_f32_e32 v5, v4
	s_nop 0
	v_fma_f32 v7, -v4, v5, 1.0
	v_fmac_f32_e32 v5, v7, v5
	v_div_scale_f32 v7, vcc, 1.0, v3, 1.0
	v_mul_f32_e32 v8, v7, v5
	v_fma_f32 v9, -v4, v8, v7
	v_fmac_f32_e32 v8, v9, v5
	v_fma_f32 v4, -v4, v8, v7
	v_div_fmas_f32 v4, v4, v5, v8
	v_div_fixup_f32 v3, v4, v3, 1.0
	ds_write_b64 v6, v[2:3]
	v_mov_b32_e32 v2, v239
	v_mov_b32_e32 v3, v247
	v_fmamk_f32 v3, v3, 0x3a800000, v164
	v_mul_f32_e32 v4, 0x4f800000, v3
	v_cmp_gt_f32_e32 vcc, s18, v3
	v_mul_f32_e32 v2, 0x3a800000, v2
	s_nop 0
	v_cndmask_b32_e32 v3, v3, v4, vcc
	v_sqrt_f32_e32 v4, v3
	s_nop 0
	v_add_u32_e32 v5, -1, v4
	v_fma_f32 v7, -v5, v4, v3
	v_add_u32_e32 v6, 1, v4
	v_cmp_ge_f32_e64 s[10:11], 0, v7
	s_nop 1
	v_cndmask_b32_e64 v5, v4, v5, s[10:11]
	v_fma_f32 v4, -v6, v4, v3
	v_cmp_lt_f32_e64 s[10:11], 0, v4
	s_nop 1
	v_cndmask_b32_e64 v4, v5, v6, s[10:11]
	v_mul_f32_e32 v5, 0x37800000, v4
	v_cndmask_b32_e32 v4, v4, v5, vcc
	v_cmp_class_f32_e32 vcc, v3, v165
	v_add_u32_e32 v6, 0x68, v77
	s_nop 0
	v_cndmask_b32_e32 v3, v4, v3, vcc
	v_div_scale_f32 v4, s[10:11], v3, v3, 1.0
	v_rcp_f32_e32 v5, v4
	s_nop 0
	v_fma_f32 v7, -v4, v5, 1.0
	v_fmac_f32_e32 v5, v7, v5
	v_div_scale_f32 v7, vcc, 1.0, v3, 1.0
	v_mul_f32_e32 v8, v7, v5
	v_fma_f32 v9, -v4, v8, v7
	v_fmac_f32_e32 v8, v9, v5
	v_fma_f32 v4, -v4, v8, v7
	v_div_fmas_f32 v4, v4, v5, v8
	v_div_fixup_f32 v3, v4, v3, 1.0
	ds_write_b64 v6, v[2:3]
	v_mov_b32_e32 v2, v240
	v_mov_b32_e32 v3, v248
	v_fmamk_f32 v3, v3, 0x3a800000, v164
	v_mul_f32_e32 v4, 0x4f800000, v3
	v_cmp_gt_f32_e32 vcc, s18, v3
	v_mul_f32_e32 v2, 0x3a800000, v2
	s_nop 0
	v_cndmask_b32_e32 v3, v3, v4, vcc
	v_sqrt_f32_e32 v4, v3
	s_nop 0
	v_add_u32_e32 v5, -1, v4
	v_fma_f32 v7, -v5, v4, v3
	v_add_u32_e32 v6, 1, v4
	v_cmp_ge_f32_e64 s[10:11], 0, v7
	s_nop 1
	v_cndmask_b32_e64 v5, v4, v5, s[10:11]
	v_fma_f32 v4, -v6, v4, v3
	v_cmp_lt_f32_e64 s[10:11], 0, v4
	s_nop 1
	v_cndmask_b32_e64 v4, v5, v6, s[10:11]
	v_mul_f32_e32 v5, 0x37800000, v4
	v_cndmask_b32_e32 v4, v4, v5, vcc
	v_cmp_class_f32_e32 vcc, v3, v165
	v_add_u32_e32 v6, 0x70, v77
	s_nop 0
	v_cndmask_b32_e32 v3, v4, v3, vcc
	v_div_scale_f32 v4, s[10:11], v3, v3, 1.0
	v_rcp_f32_e32 v5, v4
	s_nop 0
	v_fma_f32 v7, -v4, v5, 1.0
	v_fmac_f32_e32 v5, v7, v5
	v_div_scale_f32 v7, vcc, 1.0, v3, 1.0
	v_mul_f32_e32 v8, v7, v5
	v_fma_f32 v9, -v4, v8, v7
	v_fmac_f32_e32 v8, v9, v5
	v_fma_f32 v4, -v4, v8, v7
	v_div_fmas_f32 v4, v4, v5, v8
	v_div_fixup_f32 v3, v4, v3, 1.0
	ds_write_b64 v6, v[2:3]
	v_mov_b32_e32 v2, v241
	v_mov_b32_e32 v3, v249
	v_fmamk_f32 v3, v3, 0x3a800000, v164
	v_mul_f32_e32 v4, 0x4f800000, v3
	v_cmp_gt_f32_e32 vcc, s18, v3
	v_mul_f32_e32 v2, 0x3a800000, v2
	s_nop 0
	v_cndmask_b32_e32 v3, v3, v4, vcc
	v_sqrt_f32_e32 v4, v3
	s_nop 0
	v_add_u32_e32 v5, -1, v4
	v_fma_f32 v7, -v5, v4, v3
	v_add_u32_e32 v6, 1, v4
	v_cmp_ge_f32_e64 s[10:11], 0, v7
	s_nop 1
	v_cndmask_b32_e64 v5, v4, v5, s[10:11]
	v_fma_f32 v4, -v6, v4, v3
	v_cmp_lt_f32_e64 s[10:11], 0, v4
	s_nop 1
	v_cndmask_b32_e64 v4, v5, v6, s[10:11]
	v_mul_f32_e32 v5, 0x37800000, v4
	v_cndmask_b32_e32 v4, v4, v5, vcc
	v_cmp_class_f32_e32 vcc, v3, v165
	v_add_u32_e32 v6, 0x78, v77
	s_nop 0
	v_cndmask_b32_e32 v3, v4, v3, vcc
	v_div_scale_f32 v4, s[10:11], v3, v3, 1.0
	v_rcp_f32_e32 v5, v4
	s_nop 0
	v_fma_f32 v7, -v4, v5, 1.0
	v_fmac_f32_e32 v5, v7, v5
	v_div_scale_f32 v7, vcc, 1.0, v3, 1.0
	v_mul_f32_e32 v8, v7, v5
	v_fma_f32 v9, -v4, v8, v7
	v_fmac_f32_e32 v8, v9, v5
	v_fma_f32 v4, -v4, v8, v7
	v_div_fmas_f32 v4, v4, v5, v8
	v_div_fixup_f32 v3, v4, v3, 1.0
	ds_write_b64 v6, v[2:3]
	s_or_b64 exec, exec, s[16:17]
